# FFN1 and FFN2 epilogues straight from the accumulators (transposed MFMA operands, 8 and 16 byte stores, no LDS round trip)
# speedup vs baseline: 1.0224x; 1.0164x over previous
; DI int TID() { int t = (int)__builtin_amdgcn_workitem_id_x(); asm volatile("" : "+v"(t)); return t; }
; DI int BID() { int b = (int)__builtin_amdgcn_workgroup_id_x(); asm volatile("" : "+s"(b)); return b; }
; DI void tile_ffn2(const Params& p, int l, const Chunk& ck, int tile, int next, PF& pf, char* smem) {
;   float* Cs = (float*)smem;
;   const int tid = TID(); const int mi = tile & (MTN - 1), ni = tile >> MTS; const int m0 = mi * 128, n0 = ni * 128;
;   f32x16 acc[2][2]; zero_acc(acc);
;   { const u16* Ap; const u16* Wt; ffn2_ptrs(p, l, tile, Ap, Wt); gemm_run<64>(pf, Ap, 4096, Wt, acc, smem); }
;   if (next >= 0) { const u16* An; const u16* Wn; ffn2_ptrs(p, l, next, An, Wn); gemm_issue(pf, An, 4096, Wn, 4096); }
; DI void run_phase(const Params& p, int ph, int l, int c, char* smem) {
;     ...
;     default: {
;       PF pf; int t = BID();
;       if (t < MTN * 8) { const u16* A0; const u16* W0; ffn2_ptrs(p, l, t, A0, W0); gemm_issue(pf, A0, 4096, W0, 4096); }
;       for (; t < MTN * 8; t += gridDim.x) { const int tn = t + (int)gridDim.x; tile_ffn2(p, l, ck, t, tn < MTN * 8 ? tn : -1, pf, smem); }
;     } break;
.LBB1_202:
	s_andn2_b64 vcc, exec, s[22:23]
	s_cbranch_vccnz .LBB1_241
	v_readlane_b32 s16, v255, 28
	v_readlane_b32 s17, v255, 29
	s_ashr_i32 s17, s16, 31
	s_lshl_b64 s[24:25], s[16:17], 23
	s_cmp_eq_u32 s16, 0
	s_cselect_b64 s[48:49], -1, 0
	s_cmp_lg_u32 s16, 0
	s_mov_b32 s0, s16
	s_cselect_b64 s[22:23], -1, 0
	s_add_u32 s17, s18, 0x6b80000
	v_writelane_b32 v255, s0, 28
	s_addc_u32 s27, s19, 0
	s_nop 0
	v_writelane_b32 v255, s1, 29
	s_add_u32 s0, s18, s24
	s_addc_u32 s16, s19, s25
	s_add_u32 s34, s0, 0x4380000
	s_addc_u32 s40, s16, 0
	s_add_u32 s50, s18, 0x1c14c000
	s_addc_u32 s51, s19, 0
	s_add_u32 s52, s18, 0x1e14c000
	s_addc_u32 s53, s19, 0
	s_lshl_b32 s41, s26, 19
	s_lshl_b32 s24, s26, 7
	s_branch .LBB1_206
.LBB1_205:
	v_readlane_b32 s0, v255, 22
	s_add_i32 s41, s41, s0
	s_add_i32 s24, s24, s95
	s_and_b64 vcc, exec, s[28:29]
	s_mov_b32 s26, s25
	s_cbranch_vccnz .LBB1_241

; #define BLOAD(A_, B_, kt) do { _Pragma("unroll") for (int i = 0; i < 4; ++i) { \
;     A_[i] = *(const u32x4*)((const char*)Ap + (aoff + (unsigned)(32 * i * lda + (kt) * 64) * 2u)); B_[i] = *(const u32x4*)((const char*)Wt + (woff + (unsigned)(32 * i * K + (kt) * 64) * 2u)); } } while (0)
; #define BLOAD(A_, B_, kt) do { _Pragma("unroll") for (int i = 0; i < 4; ++i) { \
;     A_[i] = *(const u32x4*)((const char*)Ap + (aoff + (unsigned)(32 * i * lda + (kt) * 64) * 2u)); B_[i] = *(const u32x4*)((const char*)Wt + (woff + (unsigned)(32 * i * K + (kt) * 64) * 2u)); } } while (0)
; #define BSTORE(A_, B_, buf) do { _Pragma("unroll") for (int i = 0; i < 4; ++i) { \
;     *(u32x4*)&As[(buf) * GBUF + (srow + 32 * i) * LDT + sc8] = A_[i]; \
;     *(u32x4*)&Bs[(buf) * GBUF + (srow + 32 * i) * LDT + sc8] = B_[i]; } } while (0)
; template <int NK>
; DI void gemm_run(PF& pf, const u16* __restrict__ Ap, int lda, const u16* __restrict__ Wt, f32x16 (&acc)[2][2], char* smem) {
;     ...
;   __builtin_amdgcn_s_setprio(0);
;   __syncthreads();
;   BSTORE(pf.a0, pf.b0, 0);
;   BLOAD(pf.a0, pf.b0, 2);
;   __syncthreads();
; #pragma unroll
;   for (int kt = 0; kt < nk; kt += 2) {
;     BCOMP(0);
;     BSTORE(pf.a1, pf.b1, 1);
;     if (kt + 3 < nk) BLOAD(pf.a1, pf.b1, kt + 3);
;     __syncthreads();
;     BCOMP(1);
;     if (kt + 2 < nk) { BSTORE(pf.a0, pf.b0, 0); if (kt + 4 < nk) BLOAD(pf.a0, pf.b0, kt + 4); }
;     __syncthreads();
;   }
.Lffn2_kloop:
	s_waitcnt vmcnt(6)
	s_barrier
	ds_read_b128 v[224:227], v126 offset:0
	ds_read_b128 v[240:243], v128 offset:0
	ds_read_b128 v[244:247], v128 offset:1024
	ds_read_b128 v[248:251], v128 offset:2048
	ds_read_b128 v[156:159], v128 offset:3072
	s_add_u32 m0, s16, 0xc000
	s_add_u32 s42, s42, 0x100000
	s_addc_u32 s43, s43, 0
	global_load_lds_dwordx4 v137, s[42:43]
	global_load_lds_dwordx4 v150, s[42:43] offset:1024
	s_add_u32 m0, s0, 0xc000
	s_add_u32 s30, s30, 0x10000
	s_addc_u32 s31, s31, 0
	global_load_lds_dwordx4 v151, s[30:31]
	global_load_lds_dwordx4 v152, s[30:31] offset:1024
	global_load_lds_dwordx4 v153, s[30:31] offset:2048
	global_load_lds_dwordx4 v154, s[30:31] offset:3072
	ds_read_b128 v[228:231], v126 offset:1024
	ds_read_b128 v[232:235], v126 offset:2048
	ds_read_b128 v[236:239], v126 offset:3072
	ds_read_b128 v[160:163], v128 offset:8192
	ds_read_b128 v[164:167], v128 offset:9216
	ds_read_b128 v[168:171], v128 offset:10240
	ds_read_b128 v[122:125], v128 offset:11264
	s_waitcnt lgkmcnt(10)
	v_mfma_f32_16x16x32_bf16 v[2:5], v[240:243], v[224:227], v[2:5]
	s_waitcnt lgkmcnt(9)
	v_mfma_f32_16x16x32_bf16 v[6:9], v[244:247], v[224:227], v[6:9]
	s_waitcnt lgkmcnt(8)
	v_mfma_f32_16x16x32_bf16 v[10:13], v[248:251], v[224:227], v[10:13]
	s_waitcnt lgkmcnt(7)
	v_mfma_f32_16x16x32_bf16 v[14:17], v[156:159], v[224:227], v[14:17]
	s_waitcnt lgkmcnt(6)
	v_mfma_f32_16x16x32_bf16 v[18:21], v[240:243], v[228:231], v[18:21]
	v_mfma_f32_16x16x32_bf16 v[22:25], v[244:247], v[228:231], v[22:25]
	v_mfma_f32_16x16x32_bf16 v[26:29], v[248:251], v[228:231], v[26:29]
	v_mfma_f32_16x16x32_bf16 v[30:33], v[156:159], v[228:231], v[30:33]
	s_waitcnt lgkmcnt(5)
	v_mfma_f32_16x16x32_bf16 v[34:37], v[240:243], v[232:235], v[34:37]
	v_mfma_f32_16x16x32_bf16 v[38:41], v[244:247], v[232:235], v[38:41]
	v_mfma_f32_16x16x32_bf16 v[42:45], v[248:251], v[232:235], v[42:45]
	v_mfma_f32_16x16x32_bf16 v[46:49], v[156:159], v[232:235], v[46:49]
	s_waitcnt lgkmcnt(4)
	v_mfma_f32_16x16x32_bf16 v[50:53], v[240:243], v[236:239], v[50:53]
	v_mfma_f32_16x16x32_bf16 v[54:57], v[244:247], v[236:239], v[54:57]
	v_mfma_f32_16x16x32_bf16 v[58:61], v[248:251], v[236:239], v[58:61]
	v_mfma_f32_16x16x32_bf16 v[62:65], v[156:159], v[236:239], v[62:65]
	s_waitcnt lgkmcnt(3)
	v_mfma_f32_16x16x32_bf16 v[74:77], v[160:163], v[224:227], v[74:77]
	s_waitcnt lgkmcnt(2)
	v_mfma_f32_16x16x32_bf16 v[78:81], v[164:167], v[224:227], v[78:81]
	s_waitcnt lgkmcnt(1)
	v_mfma_f32_16x16x32_bf16 v[82:85], v[168:171], v[224:227], v[82:85]
	s_waitcnt lgkmcnt(0)
	v_mfma_f32_16x16x32_bf16 v[86:89], v[122:125], v[224:227], v[86:89]
	v_mfma_f32_16x16x32_bf16 v[90:93], v[160:163], v[228:231], v[90:93]
	v_mfma_f32_16x16x32_bf16 v[94:97], v[164:167], v[228:231], v[94:97]
	v_mfma_f32_16x16x32_bf16 v[98:101], v[168:171], v[228:231], v[98:101]
	v_mfma_f32_16x16x32_bf16 v[102:105], v[122:125], v[228:231], v[102:105]
	v_mfma_f32_16x16x32_bf16 v[106:109], v[160:163], v[232:235], v[106:109]
	v_mfma_f32_16x16x32_bf16 v[110:113], v[164:167], v[232:235], v[110:113]
	v_mfma_f32_16x16x32_bf16 v[114:117], v[168:171], v[232:235], v[114:117]
	v_mfma_f32_16x16x32_bf16 v[118:121], v[122:125], v[232:235], v[118:121]
	v_mfma_f32_16x16x32_bf16 v[208:211], v[160:163], v[236:239], v[208:211]
	v_mfma_f32_16x16x32_bf16 v[212:215], v[164:167], v[236:239], v[212:215]
	v_mfma_f32_16x16x32_bf16 v[216:219], v[168:171], v[236:239], v[216:219]
	v_mfma_f32_16x16x32_bf16 v[220:223], v[122:125], v[236:239], v[220:223]
	s_waitcnt vmcnt(6)
	s_barrier
	ds_read_b128 v[224:227], v126 offset:24576
	ds_read_b128 v[240:243], v128 offset:24576
	ds_read_b128 v[244:247], v128 offset:25600
	ds_read_b128 v[248:251], v128 offset:26624
	ds_read_b128 v[156:159], v128 offset:27648
	s_add_u32 m0, s16, 0x0
	s_add_u32 s42, s42, 0x100000
	s_addc_u32 s43, s43, 0
	global_load_lds_dwordx4 v137, s[42:43]
	global_load_lds_dwordx4 v150, s[42:43] offset:1024
	s_add_u32 m0, s0, 0x0
	s_add_u32 s30, s30, 0x10000
	s_addc_u32 s31, s31, 0
	global_load_lds_dwordx4 v151, s[30:31]
	global_load_lds_dwordx4 v152, s[30:31] offset:1024
	global_load_lds_dwordx4 v153, s[30:31] offset:2048
	global_load_lds_dwordx4 v154, s[30:31] offset:3072
	ds_read_b128 v[228:231], v126 offset:25600
	ds_read_b128 v[232:235], v126 offset:26624
	ds_read_b128 v[236:239], v126 offset:27648
	ds_read_b128 v[160:163], v128 offset:32768
	ds_read_b128 v[164:167], v128 offset:33792
	ds_read_b128 v[168:171], v128 offset:34816
	ds_read_b128 v[122:125], v128 offset:35840
	s_waitcnt lgkmcnt(10)
	v_mfma_f32_16x16x32_bf16 v[2:5], v[240:243], v[224:227], v[2:5]
	s_waitcnt lgkmcnt(9)
	v_mfma_f32_16x16x32_bf16 v[6:9], v[244:247], v[224:227], v[6:9]
	s_waitcnt lgkmcnt(8)
	v_mfma_f32_16x16x32_bf16 v[10:13], v[248:251], v[224:227], v[10:13]
	s_waitcnt lgkmcnt(7)
	v_mfma_f32_16x16x32_bf16 v[14:17], v[156:159], v[224:227], v[14:17]
	s_waitcnt lgkmcnt(6)
	v_mfma_f32_16x16x32_bf16 v[18:21], v[240:243], v[228:231], v[18:21]
	v_mfma_f32_16x16x32_bf16 v[22:25], v[244:247], v[228:231], v[22:25]
	v_mfma_f32_16x16x32_bf16 v[26:29], v[248:251], v[228:231], v[26:29]
	v_mfma_f32_16x16x32_bf16 v[30:33], v[156:159], v[228:231], v[30:33]
	s_waitcnt lgkmcnt(5)
	v_mfma_f32_16x16x32_bf16 v[34:37], v[240:243], v[232:235], v[34:37]
	v_mfma_f32_16x16x32_bf16 v[38:41], v[244:247], v[232:235], v[38:41]
	v_mfma_f32_16x16x32_bf16 v[42:45], v[248:251], v[232:235], v[42:45]
	v_mfma_f32_16x16x32_bf16 v[46:49], v[156:159], v[232:235], v[46:49]
	s_waitcnt lgkmcnt(4)
	v_mfma_f32_16x16x32_bf16 v[50:53], v[240:243], v[236:239], v[50:53]
	v_mfma_f32_16x16x32_bf16 v[54:57], v[244:247], v[236:239], v[54:57]
	v_mfma_f32_16x16x32_bf16 v[58:61], v[248:251], v[236:239], v[58:61]
	v_mfma_f32_16x16x32_bf16 v[62:65], v[156:159], v[236:239], v[62:65]
	s_waitcnt lgkmcnt(3)
	v_mfma_f32_16x16x32_bf16 v[74:77], v[160:163], v[224:227], v[74:77]
	s_waitcnt lgkmcnt(2)
	v_mfma_f32_16x16x32_bf16 v[78:81], v[164:167], v[224:227], v[78:81]
	s_waitcnt lgkmcnt(1)
	v_mfma_f32_16x16x32_bf16 v[82:85], v[168:171], v[224:227], v[82:85]
	s_waitcnt lgkmcnt(0)
	v_mfma_f32_16x16x32_bf16 v[86:89], v[122:125], v[224:227], v[86:89]
	v_mfma_f32_16x16x32_bf16 v[90:93], v[160:163], v[228:231], v[90:93]
	v_mfma_f32_16x16x32_bf16 v[94:97], v[164:167], v[228:231], v[94:97]
	v_mfma_f32_16x16x32_bf16 v[98:101], v[168:171], v[228:231], v[98:101]
	v_mfma_f32_16x16x32_bf16 v[102:105], v[122:125], v[228:231], v[102:105]
	v_mfma_f32_16x16x32_bf16 v[106:109], v[160:163], v[232:235], v[106:109]
	v_mfma_f32_16x16x32_bf16 v[110:113], v[164:167], v[232:235], v[110:113]
	v_mfma_f32_16x16x32_bf16 v[114:117], v[168:171], v[232:235], v[114:117]
	v_mfma_f32_16x16x32_bf16 v[118:121], v[122:125], v[232:235], v[118:121]
	v_mfma_f32_16x16x32_bf16 v[208:211], v[160:163], v[236:239], v[208:211]
	v_mfma_f32_16x16x32_bf16 v[212:215], v[164:167], v[236:239], v[212:215]
	v_mfma_f32_16x16x32_bf16 v[216:219], v[168:171], v[236:239], v[216:219]
	v_mfma_f32_16x16x32_bf16 v[220:223], v[122:125], v[236:239], v[220:223]
	s_waitcnt vmcnt(6)
	s_barrier
; #define BLOAD(A_, B_, kt) do { _Pragma("unroll") for (int i = 0; i < 4; ++i) { \
;     A_[i] = *(const u32x4*)((const char*)Ap + (aoff + (unsigned)(32 * i * lda + (kt) * 64) * 2u)); B_[i] = *(const u32x4*)((const char*)Wt + (woff + (unsigned)(32 * i * K + (kt) * 64) * 2u)); } } while (0)
; #define BLOAD(A_, B_, kt) do { _Pragma("unroll") for (int i = 0; i < 4; ++i) { \
;     A_[i] = *(const u32x4*)((const char*)Ap + (aoff + (unsigned)(32 * i * lda + (kt) * 64) * 2u)); B_[i] = *(const u32x4*)((const char*)Wt + (woff + (unsigned)(32 * i * K + (kt) * 64) * 2u)); } } while (0)
; #define BSTORE(A_, B_, buf) do { _Pragma("unroll") for (int i = 0; i < 4; ++i) { \
;     *(u32x4*)&As[(buf) * GBUF + (srow + 32 * i) * LDT + sc8] = A_[i]; \
;     *(u32x4*)&Bs[(buf) * GBUF + (srow + 32 * i) * LDT + sc8] = B_[i]; } } while (0)
; template <int NK>
; DI void gemm_run(PF& pf, const u16* __restrict__ Ap, int lda, const u16* __restrict__ Wt, f32x16 (&acc)[2][2], char* smem) {
;     ...
;   __builtin_amdgcn_s_setprio(0);
;   __syncthreads();
;   BSTORE(pf.a0, pf.b0, 0);
;   BLOAD(pf.a0, pf.b0, 2);
;   __syncthreads();
; #pragma unroll
;   for (int kt = 0; kt < nk; kt += 2) {
;     BCOMP(0);
;     BSTORE(pf.a1, pf.b1, 1);
;     if (kt + 3 < nk) BLOAD(pf.a1, pf.b1, kt + 3);
;     __syncthreads();
;     BCOMP(1);
;     if (kt + 2 < nk) { BSTORE(pf.a0, pf.b0, 0); if (kt + 4 < nk) BLOAD(pf.a0, pf.b0, kt + 4); }
;     __syncthreads();
;   }
	ds_read_b128 v[224:227], v126 offset:49152
	ds_read_b128 v[240:243], v128 offset:49152
	ds_read_b128 v[244:247], v128 offset:50176
	ds_read_b128 v[248:251], v128 offset:51200
	ds_read_b128 v[156:159], v128 offset:52224
	s_add_u32 m0, s16, 0x6000
	s_add_u32 s42, s42, 0x100000
	s_addc_u32 s43, s43, 0
	global_load_lds_dwordx4 v137, s[42:43]
	global_load_lds_dwordx4 v150, s[42:43] offset:1024
	s_add_u32 m0, s0, 0x6000
	s_add_u32 s30, s30, 0x10000
	s_addc_u32 s31, s31, 0
	global_load_lds_dwordx4 v151, s[30:31]
	global_load_lds_dwordx4 v152, s[30:31] offset:1024
	global_load_lds_dwordx4 v153, s[30:31] offset:2048
	global_load_lds_dwordx4 v154, s[30:31] offset:3072
	ds_read_b128 v[228:231], v126 offset:50176
	ds_read_b128 v[232:235], v126 offset:51200
	ds_read_b128 v[236:239], v126 offset:52224
	ds_read_b128 v[160:163], v128 offset:57344
	ds_read_b128 v[164:167], v128 offset:58368
	ds_read_b128 v[168:171], v128 offset:59392
	ds_read_b128 v[122:125], v128 offset:60416
	s_waitcnt lgkmcnt(10)
	v_mfma_f32_16x16x32_bf16 v[2:5], v[240:243], v[224:227], v[2:5]
	s_waitcnt lgkmcnt(9)
	v_mfma_f32_16x16x32_bf16 v[6:9], v[244:247], v[224:227], v[6:9]
	s_waitcnt lgkmcnt(8)
	v_mfma_f32_16x16x32_bf16 v[10:13], v[248:251], v[224:227], v[10:13]
	s_waitcnt lgkmcnt(7)
	v_mfma_f32_16x16x32_bf16 v[14:17], v[156:159], v[224:227], v[14:17]
	s_waitcnt lgkmcnt(6)
	v_mfma_f32_16x16x32_bf16 v[18:21], v[240:243], v[228:231], v[18:21]
	v_mfma_f32_16x16x32_bf16 v[22:25], v[244:247], v[228:231], v[22:25]
	v_mfma_f32_16x16x32_bf16 v[26:29], v[248:251], v[228:231], v[26:29]
	v_mfma_f32_16x16x32_bf16 v[30:33], v[156:159], v[228:231], v[30:33]
	s_waitcnt lgkmcnt(5)
	v_mfma_f32_16x16x32_bf16 v[34:37], v[240:243], v[232:235], v[34:37]
	v_mfma_f32_16x16x32_bf16 v[38:41], v[244:247], v[232:235], v[38:41]
	v_mfma_f32_16x16x32_bf16 v[42:45], v[248:251], v[232:235], v[42:45]
	v_mfma_f32_16x16x32_bf16 v[46:49], v[156:159], v[232:235], v[46:49]
	s_waitcnt lgkmcnt(4)
	v_mfma_f32_16x16x32_bf16 v[50:53], v[240:243], v[236:239], v[50:53]
	v_mfma_f32_16x16x32_bf16 v[54:57], v[244:247], v[236:239], v[54:57]
	v_mfma_f32_16x16x32_bf16 v[58:61], v[248:251], v[236:239], v[58:61]
	v_mfma_f32_16x16x32_bf16 v[62:65], v[156:159], v[236:239], v[62:65]
	s_waitcnt lgkmcnt(3)
	v_mfma_f32_16x16x32_bf16 v[74:77], v[160:163], v[224:227], v[74:77]
	s_waitcnt lgkmcnt(2)
	v_mfma_f32_16x16x32_bf16 v[78:81], v[164:167], v[224:227], v[78:81]
	s_waitcnt lgkmcnt(1)
	v_mfma_f32_16x16x32_bf16 v[82:85], v[168:171], v[224:227], v[82:85]
	s_waitcnt lgkmcnt(0)
	v_mfma_f32_16x16x32_bf16 v[86:89], v[122:125], v[224:227], v[86:89]
	v_mfma_f32_16x16x32_bf16 v[90:93], v[160:163], v[228:231], v[90:93]
	v_mfma_f32_16x16x32_bf16 v[94:97], v[164:167], v[228:231], v[94:97]
	v_mfma_f32_16x16x32_bf16 v[98:101], v[168:171], v[228:231], v[98:101]
	v_mfma_f32_16x16x32_bf16 v[102:105], v[122:125], v[228:231], v[102:105]
	v_mfma_f32_16x16x32_bf16 v[106:109], v[160:163], v[232:235], v[106:109]
	v_mfma_f32_16x16x32_bf16 v[110:113], v[164:167], v[232:235], v[110:113]
	v_mfma_f32_16x16x32_bf16 v[114:117], v[168:171], v[232:235], v[114:117]
	v_mfma_f32_16x16x32_bf16 v[118:121], v[122:125], v[232:235], v[118:121]
	v_mfma_f32_16x16x32_bf16 v[208:211], v[160:163], v[236:239], v[208:211]
	v_mfma_f32_16x16x32_bf16 v[212:215], v[164:167], v[236:239], v[212:215]
	v_mfma_f32_16x16x32_bf16 v[216:219], v[168:171], v[236:239], v[216:219]
	v_mfma_f32_16x16x32_bf16 v[220:223], v[122:125], v[236:239], v[220:223]
	s_sub_u32 s46, s46, 1
	s_cmp_lg_u32 s46, 0
	s_cbranch_scc1 .Lffn2_kloop
	s_waitcnt vmcnt(6)
	s_barrier
	ds_read_b128 v[224:227], v126 offset:0
	ds_read_b128 v[240:243], v128 offset:0
	ds_read_b128 v[244:247], v128 offset:1024
	ds_read_b128 v[248:251], v128 offset:2048
	ds_read_b128 v[156:159], v128 offset:3072
	ds_read_b128 v[228:231], v126 offset:1024
	ds_read_b128 v[232:235], v126 offset:2048
	ds_read_b128 v[236:239], v126 offset:3072
	ds_read_b128 v[160:163], v128 offset:8192
	ds_read_b128 v[164:167], v128 offset:9216
	ds_read_b128 v[168:171], v128 offset:10240
	ds_read_b128 v[122:125], v128 offset:11264
	s_waitcnt lgkmcnt(10)
	v_mfma_f32_16x16x32_bf16 v[2:5], v[240:243], v[224:227], v[2:5]
	s_waitcnt lgkmcnt(9)
	v_mfma_f32_16x16x32_bf16 v[6:9], v[244:247], v[224:227], v[6:9]
	s_waitcnt lgkmcnt(8)
	v_mfma_f32_16x16x32_bf16 v[10:13], v[248:251], v[224:227], v[10:13]
	s_waitcnt lgkmcnt(7)
	v_mfma_f32_16x16x32_bf16 v[14:17], v[156:159], v[224:227], v[14:17]
	s_waitcnt lgkmcnt(6)
	v_mfma_f32_16x16x32_bf16 v[18:21], v[240:243], v[228:231], v[18:21]
	v_mfma_f32_16x16x32_bf16 v[22:25], v[244:247], v[228:231], v[22:25]
	v_mfma_f32_16x16x32_bf16 v[26:29], v[248:251], v[228:231], v[26:29]
	v_mfma_f32_16x16x32_bf16 v[30:33], v[156:159], v[228:231], v[30:33]
	s_waitcnt lgkmcnt(5)
	v_mfma_f32_16x16x32_bf16 v[34:37], v[240:243], v[232:235], v[34:37]
	v_mfma_f32_16x16x32_bf16 v[38:41], v[244:247], v[232:235], v[38:41]
	v_mfma_f32_16x16x32_bf16 v[42:45], v[248:251], v[232:235], v[42:45]
	v_mfma_f32_16x16x32_bf16 v[46:49], v[156:159], v[232:235], v[46:49]
	s_waitcnt lgkmcnt(4)
	v_mfma_f32_16x16x32_bf16 v[50:53], v[240:243], v[236:239], v[50:53]
	v_mfma_f32_16x16x32_bf16 v[54:57], v[244:247], v[236:239], v[54:57]
	v_mfma_f32_16x16x32_bf16 v[58:61], v[248:251], v[236:239], v[58:61]
	v_mfma_f32_16x16x32_bf16 v[62:65], v[156:159], v[236:239], v[62:65]
	s_waitcnt lgkmcnt(3)
	v_mfma_f32_16x16x32_bf16 v[74:77], v[160:163], v[224:227], v[74:77]
	s_waitcnt lgkmcnt(2)
	v_mfma_f32_16x16x32_bf16 v[78:81], v[164:167], v[224:227], v[78:81]
	s_waitcnt lgkmcnt(1)
	v_mfma_f32_16x16x32_bf16 v[82:85], v[168:171], v[224:227], v[82:85]
	s_waitcnt lgkmcnt(0)
	v_mfma_f32_16x16x32_bf16 v[86:89], v[122:125], v[224:227], v[86:89]
	v_mfma_f32_16x16x32_bf16 v[90:93], v[160:163], v[228:231], v[90:93]
	v_mfma_f32_16x16x32_bf16 v[94:97], v[164:167], v[228:231], v[94:97]
	v_mfma_f32_16x16x32_bf16 v[98:101], v[168:171], v[228:231], v[98:101]
	v_mfma_f32_16x16x32_bf16 v[102:105], v[122:125], v[228:231], v[102:105]
	v_mfma_f32_16x16x32_bf16 v[106:109], v[160:163], v[232:235], v[106:109]
	v_mfma_f32_16x16x32_bf16 v[110:113], v[164:167], v[232:235], v[110:113]
	v_mfma_f32_16x16x32_bf16 v[114:117], v[168:171], v[232:235], v[114:117]
	v_mfma_f32_16x16x32_bf16 v[118:121], v[122:125], v[232:235], v[118:121]
	v_mfma_f32_16x16x32_bf16 v[208:211], v[160:163], v[236:239], v[208:211]
	v_mfma_f32_16x16x32_bf16 v[212:215], v[164:167], v[236:239], v[212:215]
	v_mfma_f32_16x16x32_bf16 v[216:219], v[168:171], v[236:239], v[216:219]
	v_mfma_f32_16x16x32_bf16 v[220:223], v[122:125], v[236:239], v[220:223]
	s_waitcnt vmcnt(0)
	s_barrier
; DI u32x4 pack8(const float (&v)[8]) { u32x4 r = {pk2(v[0], v[1]), pk2(v[2], v[3]), pk2(v[4], v[5]), pk2(v[6], v[7])}; return r; }
; DI void tile_ffn2(const Params& p, int l, const Chunk& ck, int tile, int next, PF& pf, char* smem) {
;     ...
;   const int row = tid >> 1, half = tid & 1; float ssq = 0.f;
;   float* xd = p.out + (size_t)(ck.tok0 + m0 + row) * 1024 + n0 + half * 64;
;   u16* xb = (u16*)(p.ws + OFF_XB) + (size_t)(m0 + row) * 1024 + n0 + half * 64;
; #pragma unroll
;   for (int c8 = 0; c8 < 8; ++c8) {
;     float v[8], x[8]; cs_ld8(Cs, row, half * 64 + c8 * 8, v); unpack8(*(const u32x4*)(xb + c8 * 8), x);
; #pragma unroll
;     for (int j = 0; j < 8; ++j) { v[j] += x[j]; ssq += v[j] * v[j]; }
;     if (l == 0) *(u32x4*)(xb + c8 * 8) = pack8(v);
;     else { *(f32x4*)(xd + c8 * 8) = f32x4{v[0], v[1], v[2], v[3]}; *(f32x4*)(xd + c8 * 8 + 4) = f32x4{v[4], v[5], v[6], v[7]}; }
;   }
;   if (l == 0) ((float*)(p.ws + OFF_PSIN))[(size_t)(m0 + row) * 16 + ni * 2 + half] = ssq;
	ds_read_b128 v[224:227], v126 offset:24576
	ds_read_b128 v[240:243], v128 offset:24576
	ds_read_b128 v[244:247], v128 offset:25600
	ds_read_b128 v[248:251], v128 offset:26624
	ds_read_b128 v[156:159], v128 offset:27648
	ds_read_b128 v[228:231], v126 offset:25600
	ds_read_b128 v[232:235], v126 offset:26624
	ds_read_b128 v[236:239], v126 offset:27648
	ds_read_b128 v[160:163], v128 offset:32768
	ds_read_b128 v[164:167], v128 offset:33792
	ds_read_b128 v[168:171], v128 offset:34816
	ds_read_b128 v[122:125], v128 offset:35840
	s_waitcnt lgkmcnt(10)
	v_mfma_f32_16x16x32_bf16 v[2:5], v[240:243], v[224:227], v[2:5]
	s_waitcnt lgkmcnt(9)
	v_mfma_f32_16x16x32_bf16 v[6:9], v[244:247], v[224:227], v[6:9]
	s_waitcnt lgkmcnt(8)
	v_mfma_f32_16x16x32_bf16 v[10:13], v[248:251], v[224:227], v[10:13]
	s_waitcnt lgkmcnt(7)
	v_mfma_f32_16x16x32_bf16 v[14:17], v[156:159], v[224:227], v[14:17]
	s_waitcnt lgkmcnt(6)
	v_mfma_f32_16x16x32_bf16 v[18:21], v[240:243], v[228:231], v[18:21]
	v_mfma_f32_16x16x32_bf16 v[22:25], v[244:247], v[228:231], v[22:25]
	v_mfma_f32_16x16x32_bf16 v[26:29], v[248:251], v[228:231], v[26:29]
	v_mfma_f32_16x16x32_bf16 v[30:33], v[156:159], v[228:231], v[30:33]
	s_waitcnt lgkmcnt(5)
	v_mfma_f32_16x16x32_bf16 v[34:37], v[240:243], v[232:235], v[34:37]
	v_mfma_f32_16x16x32_bf16 v[38:41], v[244:247], v[232:235], v[38:41]
	v_mfma_f32_16x16x32_bf16 v[42:45], v[248:251], v[232:235], v[42:45]
	v_mfma_f32_16x16x32_bf16 v[46:49], v[156:159], v[232:235], v[46:49]
	s_waitcnt lgkmcnt(4)
	v_mfma_f32_16x16x32_bf16 v[50:53], v[240:243], v[236:239], v[50:53]
	v_mfma_f32_16x16x32_bf16 v[54:57], v[244:247], v[236:239], v[54:57]
	v_mfma_f32_16x16x32_bf16 v[58:61], v[248:251], v[236:239], v[58:61]
	v_mfma_f32_16x16x32_bf16 v[62:65], v[156:159], v[236:239], v[62:65]
	s_waitcnt lgkmcnt(3)
	v_mfma_f32_16x16x32_bf16 v[74:77], v[160:163], v[224:227], v[74:77]
	s_waitcnt lgkmcnt(2)
	v_mfma_f32_16x16x32_bf16 v[78:81], v[164:167], v[224:227], v[78:81]
	s_waitcnt lgkmcnt(1)
	v_mfma_f32_16x16x32_bf16 v[82:85], v[168:171], v[224:227], v[82:85]
	s_waitcnt lgkmcnt(0)
	v_mfma_f32_16x16x32_bf16 v[86:89], v[122:125], v[224:227], v[86:89]
	v_mfma_f32_16x16x32_bf16 v[90:93], v[160:163], v[228:231], v[90:93]
	v_mfma_f32_16x16x32_bf16 v[94:97], v[164:167], v[228:231], v[94:97]
	v_mfma_f32_16x16x32_bf16 v[98:101], v[168:171], v[228:231], v[98:101]
	v_mfma_f32_16x16x32_bf16 v[102:105], v[122:125], v[228:231], v[102:105]
	v_mfma_f32_16x16x32_bf16 v[106:109], v[160:163], v[232:235], v[106:109]
	v_mfma_f32_16x16x32_bf16 v[110:113], v[164:167], v[232:235], v[110:113]
	v_mfma_f32_16x16x32_bf16 v[114:117], v[168:171], v[232:235], v[114:117]
	v_mfma_f32_16x16x32_bf16 v[118:121], v[122:125], v[232:235], v[118:121]
	v_mfma_f32_16x16x32_bf16 v[208:211], v[160:163], v[236:239], v[208:211]
	v_mfma_f32_16x16x32_bf16 v[212:215], v[164:167], v[236:239], v[212:215]
	v_mfma_f32_16x16x32_bf16 v[216:219], v[168:171], v[236:239], v[216:219]
	v_mfma_f32_16x16x32_bf16 v[220:223], v[122:125], v[236:239], v[220:223]
	s_barrier
	s_mov_b32 s16, 0
.LBB1_208:
	s_and_b32 s0, s24, 0x3f80
	v_and_b32_e32 v160, 63, v172
	v_lshrrev_b32_e32 v161, 6, v172
	v_and_b32_e32 v162, 15, v160
	v_lshrrev_b32_e32 v163, 4, v160
	v_lshrrev_b32_e32 v167, 1, v161
	v_lshl_add_u32 v167, v167, 6, v162
	v_and_b32_e32 v168, 1, v161
	v_lshlrev_b32_e32 v169, 6, v168
	v_lshl_add_u32 v169, v163, 2, v169
	v_add_u32_e32 v169, s36, v169
	v_add_u32_e32 v170, s0, v167
	v_lshlrev_b32_e32 v164, 11, v170
	v_lshl_add_u32 v164, v169, 1, v164
	v_lshlrev_b32_e32 v165, 12, v167
	v_lshl_add_u32 v165, v169, 2, v165
	v_lshlrev_b32_e32 v166, 6, v170
	v_lshl_add_u32 v166, v168, 2, v166
	s_add_i32 s0, s0, s35
	s_lshl_b32 s0, s0, 12
	s_add_u32 s12, s20, s0
	s_addc_u32 s13, s21, 0
	s_lshr_b32 s0, s36, 4
	s_add_u32 s14, s52, s0
	s_addc_u32 s15, s53, 0
	s_and_b64 vcc, exec, s[22:23]
	s_cbranch_vccnz .Lffn2_l1
	global_load_dwordx2 v[224:225], v164, s[50:51] offset:0
	global_load_dwordx2 v[226:227], v164, s[50:51] offset:32
	global_load_dwordx2 v[228:229], v164, s[50:51] offset:64
	global_load_dwordx2 v[230:231], v164, s[50:51] offset:96
	v_add_u32_e32 v164, 0x8000, v164
	global_load_dwordx2 v[232:233], v164, s[50:51] offset:0
	global_load_dwordx2 v[234:235], v164, s[50:51] offset:32
	global_load_dwordx2 v[236:237], v164, s[50:51] offset:64
	global_load_dwordx2 v[238:239], v164, s[50:51] offset:96
	v_add_u32_e32 v164, 0x8000, v164
	global_load_dwordx2 v[240:241], v164, s[50:51] offset:0
	global_load_dwordx2 v[242:243], v164, s[50:51] offset:32
	global_load_dwordx2 v[244:245], v164, s[50:51] offset:64
	global_load_dwordx2 v[246:247], v164, s[50:51] offset:96
	v_add_u32_e32 v164, 0x8000, v164
	global_load_dwordx2 v[248:249], v164, s[50:51] offset:0
	global_load_dwordx2 v[250:251], v164, s[50:51] offset:32
	global_load_dwordx2 v[156:157], v164, s[50:51] offset:64
	global_load_dwordx2 v[158:159], v164, s[50:51] offset:96
	v_subrev_u32_e32 v164, 0x18000, v164
	s_waitcnt vmcnt(0)
; DI u32x4 pack8(const float (&v)[8]) { u32x4 r = {pk2(v[0], v[1]), pk2(v[2], v[3]), pk2(v[4], v[5]), pk2(v[6], v[7])}; return r; }
; DI void tile_ffn2(const Params& p, int l, const Chunk& ck, int tile, int next, PF& pf, char* smem) {
;     ...
;   const int row = tid >> 1, half = tid & 1; float ssq = 0.f;
;   float* xd = p.out + (size_t)(ck.tok0 + m0 + row) * 1024 + n0 + half * 64;
;   u16* xb = (u16*)(p.ws + OFF_XB) + (size_t)(m0 + row) * 1024 + n0 + half * 64;
; #pragma unroll
;   for (int c8 = 0; c8 < 8; ++c8) {
;     float v[8], x[8]; cs_ld8(Cs, row, half * 64 + c8 * 8, v); unpack8(*(const u32x4*)(xb + c8 * 8), x);
; #pragma unroll
;     for (int j = 0; j < 8; ++j) { v[j] += x[j]; ssq += v[j] * v[j]; }
;     if (l == 0) *(u32x4*)(xb + c8 * 8) = pack8(v);
;     else { *(f32x4*)(xd + c8 * 8) = f32x4{v[0], v[1], v[2], v[3]}; *(f32x4*)(xd + c8 * 8 + 4) = f32x4{v[4], v[5], v[6], v[7]}; }
;   }
;   if (l == 0) ((float*)(p.ws + OFF_PSIN))[(size_t)(m0 + row) * 16 + ni * 2 + half] = ssq;
	v_mov_b32_e32 v171, 0
	v_lshlrev_b32_e32 v167, 16, v224
	v_and_b32_e32 v168, 0xffff0000, v224
	v_lshlrev_b32_e32 v169, 16, v225
	v_and_b32_e32 v170, 0xffff0000, v225
	v_add_f32_e32 v2, v2, v167
	v_add_f32_e32 v3, v3, v168
	v_add_f32_e32 v4, v4, v169
	v_add_f32_e32 v5, v5, v170
	v_fma_f32 v171, v2, v2, v171
	v_fma_f32 v171, v3, v3, v171
	v_fma_f32 v171, v4, v4, v171
	v_fma_f32 v171, v5, v5, v171
	v_cvt_pk_bf16_f32 v2, v2, v3
	v_cvt_pk_bf16_f32 v3, v4, v5
	global_store_dwordx2 v164, v[2:3], s[50:51]
	v_lshlrev_b32_e32 v167, 16, v226
	v_and_b32_e32 v168, 0xffff0000, v226
	v_lshlrev_b32_e32 v169, 16, v227
	v_and_b32_e32 v170, 0xffff0000, v227
	v_add_f32_e32 v6, v6, v167
	v_add_f32_e32 v7, v7, v168
	v_add_f32_e32 v8, v8, v169
	v_add_f32_e32 v9, v9, v170
	v_fma_f32 v171, v6, v6, v171
	v_fma_f32 v171, v7, v7, v171
	v_fma_f32 v171, v8, v8, v171
	v_fma_f32 v171, v9, v9, v171
	v_cvt_pk_bf16_f32 v6, v6, v7
	v_cvt_pk_bf16_f32 v7, v8, v9
	global_store_dwordx2 v164, v[6:7], s[50:51] offset:32
	v_lshlrev_b32_e32 v167, 16, v228
	v_and_b32_e32 v168, 0xffff0000, v228
	v_lshlrev_b32_e32 v169, 16, v229
	v_and_b32_e32 v170, 0xffff0000, v229
	v_add_f32_e32 v10, v10, v167
	v_add_f32_e32 v11, v11, v168
	v_add_f32_e32 v12, v12, v169
	v_add_f32_e32 v13, v13, v170
	v_fma_f32 v171, v10, v10, v171
	v_fma_f32 v171, v11, v11, v171
	v_fma_f32 v171, v12, v12, v171
	v_fma_f32 v171, v13, v13, v171
	v_cvt_pk_bf16_f32 v10, v10, v11
	v_cvt_pk_bf16_f32 v11, v12, v13
	global_store_dwordx2 v164, v[10:11], s[50:51] offset:64
	v_lshlrev_b32_e32 v167, 16, v230
	v_and_b32_e32 v168, 0xffff0000, v230
	v_lshlrev_b32_e32 v169, 16, v231
	v_and_b32_e32 v170, 0xffff0000, v231
	v_add_f32_e32 v14, v14, v167
	v_add_f32_e32 v15, v15, v168
	v_add_f32_e32 v16, v16, v169
	v_add_f32_e32 v17, v17, v170
	v_fma_f32 v171, v14, v14, v171
	v_fma_f32 v171, v15, v15, v171
	v_fma_f32 v171, v16, v16, v171
	v_fma_f32 v171, v17, v17, v171
	v_cvt_pk_bf16_f32 v14, v14, v15
	v_cvt_pk_bf16_f32 v15, v16, v17
	global_store_dwordx2 v164, v[14:15], s[50:51] offset:96
	v_mov_b32_e32 v167, v171
	s_nop 1
	v_permlane32_swap_b32_e32 v171, v167
	v_add_f32_e32 v171, v171, v167
	ds_swizzle_b32 v167, v171 offset:0x401f
	s_waitcnt lgkmcnt(0)
	v_add_f32_e32 v171, v171, v167
	v_cmp_gt_u32_e32 vcc, 16, v160
	s_and_saveexec_b64 s[98:99], vcc
	global_store_dword v166, v171, s[14:15] offset:0
	s_or_b64 exec, exec, s[98:99]
	v_add_u32_e32 v164, 0x8000, v164
	v_mov_b32_e32 v171, 0
	v_lshlrev_b32_e32 v167, 16, v232
	v_and_b32_e32 v168, 0xffff0000, v232
	v_lshlrev_b32_e32 v169, 16, v233
	v_and_b32_e32 v170, 0xffff0000, v233
	v_add_f32_e32 v18, v18, v167
	v_add_f32_e32 v19, v19, v168
	v_add_f32_e32 v20, v20, v169
	v_add_f32_e32 v21, v21, v170
	v_fma_f32 v171, v18, v18, v171
	v_fma_f32 v171, v19, v19, v171
	v_fma_f32 v171, v20, v20, v171
	v_fma_f32 v171, v21, v21, v171
	v_cvt_pk_bf16_f32 v18, v18, v19
	v_cvt_pk_bf16_f32 v19, v20, v21
	global_store_dwordx2 v164, v[18:19], s[50:51]
	v_lshlrev_b32_e32 v167, 16, v234
	v_and_b32_e32 v168, 0xffff0000, v234
	v_lshlrev_b32_e32 v169, 16, v235
	v_and_b32_e32 v170, 0xffff0000, v235
	v_add_f32_e32 v22, v22, v167
	v_add_f32_e32 v23, v23, v168
	v_add_f32_e32 v24, v24, v169
	v_add_f32_e32 v25, v25, v170
	v_fma_f32 v171, v22, v22, v171
	v_fma_f32 v171, v23, v23, v171
	v_fma_f32 v171, v24, v24, v171
	v_fma_f32 v171, v25, v25, v171
	v_cvt_pk_bf16_f32 v22, v22, v23
	v_cvt_pk_bf16_f32 v23, v24, v25
	global_store_dwordx2 v164, v[22:23], s[50:51] offset:32
	v_lshlrev_b32_e32 v167, 16, v236
	v_and_b32_e32 v168, 0xffff0000, v236
	v_lshlrev_b32_e32 v169, 16, v237
	v_and_b32_e32 v170, 0xffff0000, v237
	v_add_f32_e32 v26, v26, v167
	v_add_f32_e32 v27, v27, v168
	v_add_f32_e32 v28, v28, v169
	v_add_f32_e32 v29, v29, v170
	v_fma_f32 v171, v26, v26, v171
	v_fma_f32 v171, v27, v27, v171
	v_fma_f32 v171, v28, v28, v171
	v_fma_f32 v171, v29, v29, v171
	v_cvt_pk_bf16_f32 v26, v26, v27
	v_cvt_pk_bf16_f32 v27, v28, v29
	global_store_dwordx2 v164, v[26:27], s[50:51] offset:64
	v_lshlrev_b32_e32 v167, 16, v238
	v_and_b32_e32 v168, 0xffff0000, v238
	v_lshlrev_b32_e32 v169, 16, v239
	v_and_b32_e32 v170, 0xffff0000, v239
	v_add_f32_e32 v30, v30, v167
	v_add_f32_e32 v31, v31, v168
	v_add_f32_e32 v32, v32, v169
	v_add_f32_e32 v33, v33, v170
	v_fma_f32 v171, v30, v30, v171
	v_fma_f32 v171, v31, v31, v171
	v_fma_f32 v171, v32, v32, v171
	v_fma_f32 v171, v33, v33, v171
	v_cvt_pk_bf16_f32 v30, v30, v31
	v_cvt_pk_bf16_f32 v31, v32, v33
	global_store_dwordx2 v164, v[30:31], s[50:51] offset:96
	v_mov_b32_e32 v167, v171
	s_nop 1
	v_permlane32_swap_b32_e32 v171, v167
	v_add_f32_e32 v171, v171, v167
	ds_swizzle_b32 v167, v171 offset:0x401f
	s_waitcnt lgkmcnt(0)
; DI u32x4 pack8(const float (&v)[8]) { u32x4 r = {pk2(v[0], v[1]), pk2(v[2], v[3]), pk2(v[4], v[5]), pk2(v[6], v[7])}; return r; }
; DI void tile_ffn2(const Params& p, int l, const Chunk& ck, int tile, int next, PF& pf, char* smem) {
;     ...
;   const int row = tid >> 1, half = tid & 1; float ssq = 0.f;
;   float* xd = p.out + (size_t)(ck.tok0 + m0 + row) * 1024 + n0 + half * 64;
;   u16* xb = (u16*)(p.ws + OFF_XB) + (size_t)(m0 + row) * 1024 + n0 + half * 64;
; #pragma unroll
;   for (int c8 = 0; c8 < 8; ++c8) {
;     float v[8], x[8]; cs_ld8(Cs, row, half * 64 + c8 * 8, v); unpack8(*(const u32x4*)(xb + c8 * 8), x);
; #pragma unroll
;     for (int j = 0; j < 8; ++j) { v[j] += x[j]; ssq += v[j] * v[j]; }
;     if (l == 0) *(u32x4*)(xb + c8 * 8) = pack8(v);
;     else { *(f32x4*)(xd + c8 * 8) = f32x4{v[0], v[1], v[2], v[3]}; *(f32x4*)(xd + c8 * 8 + 4) = f32x4{v[4], v[5], v[6], v[7]}; }
;   }
;   if (l == 0) ((float*)(p.ws + OFF_PSIN))[(size_t)(m0 + row) * 16 + ni * 2 + half] = ssq;
	v_add_f32_e32 v171, v171, v167
	v_cmp_gt_u32_e32 vcc, 16, v160
	s_and_saveexec_b64 s[98:99], vcc
	global_store_dword v166, v171, s[14:15] offset:1024
	s_or_b64 exec, exec, s[98:99]
	v_add_u32_e32 v164, 0x8000, v164
	v_mov_b32_e32 v171, 0
	v_lshlrev_b32_e32 v167, 16, v240
	v_and_b32_e32 v168, 0xffff0000, v240
	v_lshlrev_b32_e32 v169, 16, v241
	v_and_b32_e32 v170, 0xffff0000, v241
	v_add_f32_e32 v34, v34, v167
	v_add_f32_e32 v35, v35, v168
	v_add_f32_e32 v36, v36, v169
	v_add_f32_e32 v37, v37, v170
	v_fma_f32 v171, v34, v34, v171
	v_fma_f32 v171, v35, v35, v171
	v_fma_f32 v171, v36, v36, v171
	v_fma_f32 v171, v37, v37, v171
	v_cvt_pk_bf16_f32 v34, v34, v35
	v_cvt_pk_bf16_f32 v35, v36, v37
	global_store_dwordx2 v164, v[34:35], s[50:51]
	v_lshlrev_b32_e32 v167, 16, v242
	v_and_b32_e32 v168, 0xffff0000, v242
	v_lshlrev_b32_e32 v169, 16, v243
	v_and_b32_e32 v170, 0xffff0000, v243
	v_add_f32_e32 v38, v38, v167
	v_add_f32_e32 v39, v39, v168
	v_add_f32_e32 v40, v40, v169
	v_add_f32_e32 v41, v41, v170
	v_fma_f32 v171, v38, v38, v171
	v_fma_f32 v171, v39, v39, v171
	v_fma_f32 v171, v40, v40, v171
	v_fma_f32 v171, v41, v41, v171
	v_cvt_pk_bf16_f32 v38, v38, v39
	v_cvt_pk_bf16_f32 v39, v40, v41
	global_store_dwordx2 v164, v[38:39], s[50:51] offset:32
	v_lshlrev_b32_e32 v167, 16, v244
	v_and_b32_e32 v168, 0xffff0000, v244
	v_lshlrev_b32_e32 v169, 16, v245
	v_and_b32_e32 v170, 0xffff0000, v245
	v_add_f32_e32 v42, v42, v167
	v_add_f32_e32 v43, v43, v168
	v_add_f32_e32 v44, v44, v169
	v_add_f32_e32 v45, v45, v170
	v_fma_f32 v171, v42, v42, v171
	v_fma_f32 v171, v43, v43, v171
	v_fma_f32 v171, v44, v44, v171
	v_fma_f32 v171, v45, v45, v171
	v_cvt_pk_bf16_f32 v42, v42, v43
	v_cvt_pk_bf16_f32 v43, v44, v45
	global_store_dwordx2 v164, v[42:43], s[50:51] offset:64
	v_lshlrev_b32_e32 v167, 16, v246
	v_and_b32_e32 v168, 0xffff0000, v246
	v_lshlrev_b32_e32 v169, 16, v247
	v_and_b32_e32 v170, 0xffff0000, v247
	v_add_f32_e32 v46, v46, v167
	v_add_f32_e32 v47, v47, v168
	v_add_f32_e32 v48, v48, v169
	v_add_f32_e32 v49, v49, v170
	v_fma_f32 v171, v46, v46, v171
	v_fma_f32 v171, v47, v47, v171
	v_fma_f32 v171, v48, v48, v171
	v_fma_f32 v171, v49, v49, v171
	v_cvt_pk_bf16_f32 v46, v46, v47
	v_cvt_pk_bf16_f32 v47, v48, v49
	global_store_dwordx2 v164, v[46:47], s[50:51] offset:96
	v_mov_b32_e32 v167, v171
	s_nop 1
	v_permlane32_swap_b32_e32 v171, v167
	v_add_f32_e32 v171, v171, v167
	ds_swizzle_b32 v167, v171 offset:0x401f
	s_waitcnt lgkmcnt(0)
	v_add_f32_e32 v171, v171, v167
	v_cmp_gt_u32_e32 vcc, 16, v160
	s_and_saveexec_b64 s[98:99], vcc
	global_store_dword v166, v171, s[14:15] offset:2048
	s_or_b64 exec, exec, s[98:99]
	v_add_u32_e32 v164, 0x8000, v164
	v_mov_b32_e32 v171, 0
	v_lshlrev_b32_e32 v167, 16, v248
	v_and_b32_e32 v168, 0xffff0000, v248
	v_lshlrev_b32_e32 v169, 16, v249
	v_and_b32_e32 v170, 0xffff0000, v249
	v_add_f32_e32 v50, v50, v167
	v_add_f32_e32 v51, v51, v168
	v_add_f32_e32 v52, v52, v169
	v_add_f32_e32 v53, v53, v170
	v_fma_f32 v171, v50, v50, v171
	v_fma_f32 v171, v51, v51, v171
	v_fma_f32 v171, v52, v52, v171
	v_fma_f32 v171, v53, v53, v171
	v_cvt_pk_bf16_f32 v50, v50, v51
	v_cvt_pk_bf16_f32 v51, v52, v53
	global_store_dwordx2 v164, v[50:51], s[50:51]
	v_lshlrev_b32_e32 v167, 16, v250
	v_and_b32_e32 v168, 0xffff0000, v250
	v_lshlrev_b32_e32 v169, 16, v251
	v_and_b32_e32 v170, 0xffff0000, v251
	v_add_f32_e32 v54, v54, v167
	v_add_f32_e32 v55, v55, v168
	v_add_f32_e32 v56, v56, v169
	v_add_f32_e32 v57, v57, v170
	v_fma_f32 v171, v54, v54, v171
	v_fma_f32 v171, v55, v55, v171
	v_fma_f32 v171, v56, v56, v171
	v_fma_f32 v171, v57, v57, v171
	v_cvt_pk_bf16_f32 v54, v54, v55
	v_cvt_pk_bf16_f32 v55, v56, v57
	global_store_dwordx2 v164, v[54:55], s[50:51] offset:32
	v_lshlrev_b32_e32 v167, 16, v156
	v_and_b32_e32 v168, 0xffff0000, v156
	v_lshlrev_b32_e32 v169, 16, v157
	v_and_b32_e32 v170, 0xffff0000, v157
	v_add_f32_e32 v58, v58, v167
	v_add_f32_e32 v59, v59, v168
	v_add_f32_e32 v60, v60, v169
	v_add_f32_e32 v61, v61, v170
	v_fma_f32 v171, v58, v58, v171
	v_fma_f32 v171, v59, v59, v171
	v_fma_f32 v171, v60, v60, v171
	v_fma_f32 v171, v61, v61, v171
	v_cvt_pk_bf16_f32 v58, v58, v59
	v_cvt_pk_bf16_f32 v59, v60, v61
	global_store_dwordx2 v164, v[58:59], s[50:51] offset:64
	v_lshlrev_b32_e32 v167, 16, v158
	v_and_b32_e32 v168, 0xffff0000, v158
	v_lshlrev_b32_e32 v169, 16, v159
	v_and_b32_e32 v170, 0xffff0000, v159
	v_add_f32_e32 v62, v62, v167
	v_add_f32_e32 v63, v63, v168
	v_add_f32_e32 v64, v64, v169
	v_add_f32_e32 v65, v65, v170
	v_fma_f32 v171, v62, v62, v171
	v_fma_f32 v171, v63, v63, v171
	v_fma_f32 v171, v64, v64, v171
	v_fma_f32 v171, v65, v65, v171
	v_cvt_pk_bf16_f32 v62, v62, v63
	v_cvt_pk_bf16_f32 v63, v64, v65
	global_store_dwordx2 v164, v[62:63], s[50:51] offset:96
	v_mov_b32_e32 v167, v171
	s_nop 1
	v_permlane32_swap_b32_e32 v171, v167
	v_add_f32_e32 v171, v171, v167
	ds_swizzle_b32 v167, v171 offset:0x401f
	s_waitcnt lgkmcnt(0)
	v_add_f32_e32 v171, v171, v167
	v_cmp_gt_u32_e32 vcc, 16, v160
	s_and_saveexec_b64 s[98:99], vcc
	global_store_dword v166, v171, s[14:15] offset:3072
	s_or_b64 exec, exec, s[98:99]
	v_subrev_u32_e32 v164, 0x18000, v164
	global_load_dwordx2 v[224:225], v164, s[50:51] offset:256
	global_load_dwordx2 v[226:227], v164, s[50:51] offset:288
	global_load_dwordx2 v[228:229], v164, s[50:51] offset:320
	global_load_dwordx2 v[230:231], v164, s[50:51] offset:352
	v_add_u32_e32 v164, 0x8000, v164
	global_load_dwordx2 v[232:233], v164, s[50:51] offset:256
	global_load_dwordx2 v[234:235], v164, s[50:51] offset:288
	global_load_dwordx2 v[236:237], v164, s[50:51] offset:320
	global_load_dwordx2 v[238:239], v164, s[50:51] offset:352
	v_add_u32_e32 v164, 0x8000, v164
	global_load_dwordx2 v[240:241], v164, s[50:51] offset:256
	global_load_dwordx2 v[242:243], v164, s[50:51] offset:288
	global_load_dwordx2 v[244:245], v164, s[50:51] offset:320
	global_load_dwordx2 v[246:247], v164, s[50:51] offset:352
	v_add_u32_e32 v164, 0x8000, v164
	global_load_dwordx2 v[248:249], v164, s[50:51] offset:256
	global_load_dwordx2 v[250:251], v164, s[50:51] offset:288
	global_load_dwordx2 v[156:157], v164, s[50:51] offset:320
	global_load_dwordx2 v[158:159], v164, s[50:51] offset:352
	v_subrev_u32_e32 v164, 0x18000, v164
	s_waitcnt vmcnt(0)
; DI u32x4 pack8(const float (&v)[8]) { u32x4 r = {pk2(v[0], v[1]), pk2(v[2], v[3]), pk2(v[4], v[5]), pk2(v[6], v[7])}; return r; }
; DI void tile_ffn2(const Params& p, int l, const Chunk& ck, int tile, int next, PF& pf, char* smem) {
;     ...
;   const int row = tid >> 1, half = tid & 1; float ssq = 0.f;
;   float* xd = p.out + (size_t)(ck.tok0 + m0 + row) * 1024 + n0 + half * 64;
;   u16* xb = (u16*)(p.ws + OFF_XB) + (size_t)(m0 + row) * 1024 + n0 + half * 64;
; #pragma unroll
;   for (int c8 = 0; c8 < 8; ++c8) {
;     float v[8], x[8]; cs_ld8(Cs, row, half * 64 + c8 * 8, v); unpack8(*(const u32x4*)(xb + c8 * 8), x);
; #pragma unroll
;     for (int j = 0; j < 8; ++j) { v[j] += x[j]; ssq += v[j] * v[j]; }
;     if (l == 0) *(u32x4*)(xb + c8 * 8) = pack8(v);
;     else { *(f32x4*)(xd + c8 * 8) = f32x4{v[0], v[1], v[2], v[3]}; *(f32x4*)(xd + c8 * 8 + 4) = f32x4{v[4], v[5], v[6], v[7]}; }
;   }
;   if (l == 0) ((float*)(p.ws + OFF_PSIN))[(size_t)(m0 + row) * 16 + ni * 2 + half] = ssq;
	v_mov_b32_e32 v171, 0
	v_lshlrev_b32_e32 v167, 16, v224
	v_and_b32_e32 v168, 0xffff0000, v224
	v_lshlrev_b32_e32 v169, 16, v225
	v_and_b32_e32 v170, 0xffff0000, v225
	v_add_f32_e32 v74, v74, v167
	v_add_f32_e32 v75, v75, v168
	v_add_f32_e32 v76, v76, v169
	v_add_f32_e32 v77, v77, v170
	v_fma_f32 v171, v74, v74, v171
	v_fma_f32 v171, v75, v75, v171
	v_fma_f32 v171, v76, v76, v171
	v_fma_f32 v171, v77, v77, v171
	v_cvt_pk_bf16_f32 v74, v74, v75
	v_cvt_pk_bf16_f32 v75, v76, v77
	global_store_dwordx2 v164, v[74:75], s[50:51] offset:256
	v_lshlrev_b32_e32 v167, 16, v226
	v_and_b32_e32 v168, 0xffff0000, v226
	v_lshlrev_b32_e32 v169, 16, v227
	v_and_b32_e32 v170, 0xffff0000, v227
	v_add_f32_e32 v78, v78, v167
	v_add_f32_e32 v79, v79, v168
	v_add_f32_e32 v80, v80, v169
	v_add_f32_e32 v81, v81, v170
	v_fma_f32 v171, v78, v78, v171
	v_fma_f32 v171, v79, v79, v171
	v_fma_f32 v171, v80, v80, v171
	v_fma_f32 v171, v81, v81, v171
	v_cvt_pk_bf16_f32 v78, v78, v79
	v_cvt_pk_bf16_f32 v79, v80, v81
	global_store_dwordx2 v164, v[78:79], s[50:51] offset:288
	v_lshlrev_b32_e32 v167, 16, v228
	v_and_b32_e32 v168, 0xffff0000, v228
	v_lshlrev_b32_e32 v169, 16, v229
	v_and_b32_e32 v170, 0xffff0000, v229
	v_add_f32_e32 v82, v82, v167
	v_add_f32_e32 v83, v83, v168
	v_add_f32_e32 v84, v84, v169
	v_add_f32_e32 v85, v85, v170
	v_fma_f32 v171, v82, v82, v171
	v_fma_f32 v171, v83, v83, v171
	v_fma_f32 v171, v84, v84, v171
	v_fma_f32 v171, v85, v85, v171
	v_cvt_pk_bf16_f32 v82, v82, v83
	v_cvt_pk_bf16_f32 v83, v84, v85
	global_store_dwordx2 v164, v[82:83], s[50:51] offset:320
	v_lshlrev_b32_e32 v167, 16, v230
	v_and_b32_e32 v168, 0xffff0000, v230
	v_lshlrev_b32_e32 v169, 16, v231
	v_and_b32_e32 v170, 0xffff0000, v231
	v_add_f32_e32 v86, v86, v167
	v_add_f32_e32 v87, v87, v168
	v_add_f32_e32 v88, v88, v169
	v_add_f32_e32 v89, v89, v170
	v_fma_f32 v171, v86, v86, v171
	v_fma_f32 v171, v87, v87, v171
	v_fma_f32 v171, v88, v88, v171
	v_fma_f32 v171, v89, v89, v171
	v_cvt_pk_bf16_f32 v86, v86, v87
	v_cvt_pk_bf16_f32 v87, v88, v89
	global_store_dwordx2 v164, v[86:87], s[50:51] offset:352
	v_mov_b32_e32 v167, v171
	s_nop 1
	v_permlane32_swap_b32_e32 v171, v167
	v_add_f32_e32 v171, v171, v167
	ds_swizzle_b32 v167, v171 offset:0x401f
	s_waitcnt lgkmcnt(0)
	v_add_f32_e32 v171, v171, v167
	v_cmp_gt_u32_e32 vcc, 16, v160
	s_and_saveexec_b64 s[98:99], vcc
	global_store_dword v166, v171, s[14:15] offset:8
	s_or_b64 exec, exec, s[98:99]
	v_add_u32_e32 v164, 0x8000, v164
	v_mov_b32_e32 v171, 0
	v_lshlrev_b32_e32 v167, 16, v232
	v_and_b32_e32 v168, 0xffff0000, v232
	v_lshlrev_b32_e32 v169, 16, v233
	v_and_b32_e32 v170, 0xffff0000, v233
	v_add_f32_e32 v90, v90, v167
	v_add_f32_e32 v91, v91, v168
	v_add_f32_e32 v92, v92, v169
	v_add_f32_e32 v93, v93, v170
	v_fma_f32 v171, v90, v90, v171
	v_fma_f32 v171, v91, v91, v171
	v_fma_f32 v171, v92, v92, v171
	v_fma_f32 v171, v93, v93, v171
	v_cvt_pk_bf16_f32 v90, v90, v91
	v_cvt_pk_bf16_f32 v91, v92, v93
	global_store_dwordx2 v164, v[90:91], s[50:51] offset:256
	v_lshlrev_b32_e32 v167, 16, v234
	v_and_b32_e32 v168, 0xffff0000, v234
	v_lshlrev_b32_e32 v169, 16, v235
	v_and_b32_e32 v170, 0xffff0000, v235
	v_add_f32_e32 v94, v94, v167
	v_add_f32_e32 v95, v95, v168
	v_add_f32_e32 v96, v96, v169
	v_add_f32_e32 v97, v97, v170
	v_fma_f32 v171, v94, v94, v171
	v_fma_f32 v171, v95, v95, v171
	v_fma_f32 v171, v96, v96, v171
	v_fma_f32 v171, v97, v97, v171
	v_cvt_pk_bf16_f32 v94, v94, v95
	v_cvt_pk_bf16_f32 v95, v96, v97
	global_store_dwordx2 v164, v[94:95], s[50:51] offset:288
	v_lshlrev_b32_e32 v167, 16, v236
	v_and_b32_e32 v168, 0xffff0000, v236
	v_lshlrev_b32_e32 v169, 16, v237
	v_and_b32_e32 v170, 0xffff0000, v237
	v_add_f32_e32 v98, v98, v167
	v_add_f32_e32 v99, v99, v168
	v_add_f32_e32 v100, v100, v169
	v_add_f32_e32 v101, v101, v170
	v_fma_f32 v171, v98, v98, v171
	v_fma_f32 v171, v99, v99, v171
	v_fma_f32 v171, v100, v100, v171
	v_fma_f32 v171, v101, v101, v171
	v_cvt_pk_bf16_f32 v98, v98, v99
	v_cvt_pk_bf16_f32 v99, v100, v101
	global_store_dwordx2 v164, v[98:99], s[50:51] offset:320
	v_lshlrev_b32_e32 v167, 16, v238
	v_and_b32_e32 v168, 0xffff0000, v238
	v_lshlrev_b32_e32 v169, 16, v239
	v_and_b32_e32 v170, 0xffff0000, v239
	v_add_f32_e32 v102, v102, v167
	v_add_f32_e32 v103, v103, v168
	v_add_f32_e32 v104, v104, v169
	v_add_f32_e32 v105, v105, v170
	v_fma_f32 v171, v102, v102, v171
	v_fma_f32 v171, v103, v103, v171
	v_fma_f32 v171, v104, v104, v171
	v_fma_f32 v171, v105, v105, v171
	v_cvt_pk_bf16_f32 v102, v102, v103
	v_cvt_pk_bf16_f32 v103, v104, v105
	global_store_dwordx2 v164, v[102:103], s[50:51] offset:352
	v_mov_b32_e32 v167, v171
	s_nop 1
	v_permlane32_swap_b32_e32 v171, v167
	v_add_f32_e32 v171, v171, v167
	ds_swizzle_b32 v167, v171 offset:0x401f
	s_waitcnt lgkmcnt(0)
; DI u32x4 pack8(const float (&v)[8]) { u32x4 r = {pk2(v[0], v[1]), pk2(v[2], v[3]), pk2(v[4], v[5]), pk2(v[6], v[7])}; return r; }
; DI void tile_ffn2(const Params& p, int l, const Chunk& ck, int tile, int next, PF& pf, char* smem) {
;     ...
;   const int row = tid >> 1, half = tid & 1; float ssq = 0.f;
;   float* xd = p.out + (size_t)(ck.tok0 + m0 + row) * 1024 + n0 + half * 64;
;   u16* xb = (u16*)(p.ws + OFF_XB) + (size_t)(m0 + row) * 1024 + n0 + half * 64;
; #pragma unroll
;   for (int c8 = 0; c8 < 8; ++c8) {
;     float v[8], x[8]; cs_ld8(Cs, row, half * 64 + c8 * 8, v); unpack8(*(const u32x4*)(xb + c8 * 8), x);
; #pragma unroll
;     for (int j = 0; j < 8; ++j) { v[j] += x[j]; ssq += v[j] * v[j]; }
;     if (l == 0) *(u32x4*)(xb + c8 * 8) = pack8(v);
;     else { *(f32x4*)(xd + c8 * 8) = f32x4{v[0], v[1], v[2], v[3]}; *(f32x4*)(xd + c8 * 8 + 4) = f32x4{v[4], v[5], v[6], v[7]}; }
;   }
;   if (l == 0) ((float*)(p.ws + OFF_PSIN))[(size_t)(m0 + row) * 16 + ni * 2 + half] = ssq;
	v_add_f32_e32 v171, v171, v167
	v_cmp_gt_u32_e32 vcc, 16, v160
	s_and_saveexec_b64 s[98:99], vcc
	global_store_dword v166, v171, s[14:15] offset:1032
	s_or_b64 exec, exec, s[98:99]
	v_add_u32_e32 v164, 0x8000, v164
	v_mov_b32_e32 v171, 0
	v_lshlrev_b32_e32 v167, 16, v240
	v_and_b32_e32 v168, 0xffff0000, v240
	v_lshlrev_b32_e32 v169, 16, v241
	v_and_b32_e32 v170, 0xffff0000, v241
	v_add_f32_e32 v106, v106, v167
	v_add_f32_e32 v107, v107, v168
	v_add_f32_e32 v108, v108, v169
	v_add_f32_e32 v109, v109, v170
	v_fma_f32 v171, v106, v106, v171
	v_fma_f32 v171, v107, v107, v171
	v_fma_f32 v171, v108, v108, v171
	v_fma_f32 v171, v109, v109, v171
	v_cvt_pk_bf16_f32 v106, v106, v107
	v_cvt_pk_bf16_f32 v107, v108, v109
	global_store_dwordx2 v164, v[106:107], s[50:51] offset:256
	v_lshlrev_b32_e32 v167, 16, v242
	v_and_b32_e32 v168, 0xffff0000, v242
	v_lshlrev_b32_e32 v169, 16, v243
	v_and_b32_e32 v170, 0xffff0000, v243
	v_add_f32_e32 v110, v110, v167
	v_add_f32_e32 v111, v111, v168
	v_add_f32_e32 v112, v112, v169
	v_add_f32_e32 v113, v113, v170
	v_fma_f32 v171, v110, v110, v171
	v_fma_f32 v171, v111, v111, v171
	v_fma_f32 v171, v112, v112, v171
	v_fma_f32 v171, v113, v113, v171
	v_cvt_pk_bf16_f32 v110, v110, v111
	v_cvt_pk_bf16_f32 v111, v112, v113
	global_store_dwordx2 v164, v[110:111], s[50:51] offset:288
	v_lshlrev_b32_e32 v167, 16, v244
	v_and_b32_e32 v168, 0xffff0000, v244
	v_lshlrev_b32_e32 v169, 16, v245
	v_and_b32_e32 v170, 0xffff0000, v245
	v_add_f32_e32 v114, v114, v167
	v_add_f32_e32 v115, v115, v168
	v_add_f32_e32 v116, v116, v169
	v_add_f32_e32 v117, v117, v170
	v_fma_f32 v171, v114, v114, v171
	v_fma_f32 v171, v115, v115, v171
	v_fma_f32 v171, v116, v116, v171
	v_fma_f32 v171, v117, v117, v171
	v_cvt_pk_bf16_f32 v114, v114, v115
	v_cvt_pk_bf16_f32 v115, v116, v117
	global_store_dwordx2 v164, v[114:115], s[50:51] offset:320
	v_lshlrev_b32_e32 v167, 16, v246
	v_and_b32_e32 v168, 0xffff0000, v246
	v_lshlrev_b32_e32 v169, 16, v247
	v_and_b32_e32 v170, 0xffff0000, v247
	v_add_f32_e32 v118, v118, v167
	v_add_f32_e32 v119, v119, v168
	v_add_f32_e32 v120, v120, v169
	v_add_f32_e32 v121, v121, v170
	v_fma_f32 v171, v118, v118, v171
	v_fma_f32 v171, v119, v119, v171
	v_fma_f32 v171, v120, v120, v171
	v_fma_f32 v171, v121, v121, v171
	v_cvt_pk_bf16_f32 v118, v118, v119
	v_cvt_pk_bf16_f32 v119, v120, v121
	global_store_dwordx2 v164, v[118:119], s[50:51] offset:352
	v_mov_b32_e32 v167, v171
	s_nop 1
	v_permlane32_swap_b32_e32 v171, v167
	v_add_f32_e32 v171, v171, v167
	ds_swizzle_b32 v167, v171 offset:0x401f
	s_waitcnt lgkmcnt(0)
	v_add_f32_e32 v171, v171, v167
	v_cmp_gt_u32_e32 vcc, 16, v160
	s_and_saveexec_b64 s[98:99], vcc
	global_store_dword v166, v171, s[14:15] offset:2056
	s_or_b64 exec, exec, s[98:99]
	v_add_u32_e32 v164, 0x8000, v164
	v_mov_b32_e32 v171, 0
	v_lshlrev_b32_e32 v167, 16, v248
	v_and_b32_e32 v168, 0xffff0000, v248
	v_lshlrev_b32_e32 v169, 16, v249
	v_and_b32_e32 v170, 0xffff0000, v249
	v_add_f32_e32 v208, v208, v167
	v_add_f32_e32 v209, v209, v168
	v_add_f32_e32 v210, v210, v169
	v_add_f32_e32 v211, v211, v170
	v_fma_f32 v171, v208, v208, v171
	v_fma_f32 v171, v209, v209, v171
	v_fma_f32 v171, v210, v210, v171
	v_fma_f32 v171, v211, v211, v171
	v_cvt_pk_bf16_f32 v208, v208, v209
	v_cvt_pk_bf16_f32 v209, v210, v211
	global_store_dwordx2 v164, v[208:209], s[50:51] offset:256
	v_lshlrev_b32_e32 v167, 16, v250
	v_and_b32_e32 v168, 0xffff0000, v250
	v_lshlrev_b32_e32 v169, 16, v251
	v_and_b32_e32 v170, 0xffff0000, v251
	v_add_f32_e32 v212, v212, v167
	v_add_f32_e32 v213, v213, v168
	v_add_f32_e32 v214, v214, v169
	v_add_f32_e32 v215, v215, v170
	v_fma_f32 v171, v212, v212, v171
	v_fma_f32 v171, v213, v213, v171
	v_fma_f32 v171, v214, v214, v171
	v_fma_f32 v171, v215, v215, v171
	v_cvt_pk_bf16_f32 v212, v212, v213
	v_cvt_pk_bf16_f32 v213, v214, v215
	global_store_dwordx2 v164, v[212:213], s[50:51] offset:288
	v_lshlrev_b32_e32 v167, 16, v156
	v_and_b32_e32 v168, 0xffff0000, v156
	v_lshlrev_b32_e32 v169, 16, v157
	v_and_b32_e32 v170, 0xffff0000, v157
	v_add_f32_e32 v216, v216, v167
	v_add_f32_e32 v217, v217, v168
	v_add_f32_e32 v218, v218, v169
	v_add_f32_e32 v219, v219, v170
	v_fma_f32 v171, v216, v216, v171
	v_fma_f32 v171, v217, v217, v171
	v_fma_f32 v171, v218, v218, v171
	v_fma_f32 v171, v219, v219, v171
	v_cvt_pk_bf16_f32 v216, v216, v217
	v_cvt_pk_bf16_f32 v217, v218, v219
	global_store_dwordx2 v164, v[216:217], s[50:51] offset:320
	v_lshlrev_b32_e32 v167, 16, v158
	v_and_b32_e32 v168, 0xffff0000, v158
	v_lshlrev_b32_e32 v169, 16, v159
	v_and_b32_e32 v170, 0xffff0000, v159
	v_add_f32_e32 v220, v220, v167
	v_add_f32_e32 v221, v221, v168
	v_add_f32_e32 v222, v222, v169
	v_add_f32_e32 v223, v223, v170
	v_fma_f32 v171, v220, v220, v171
	v_fma_f32 v171, v221, v221, v171
	v_fma_f32 v171, v222, v222, v171
	v_fma_f32 v171, v223, v223, v171
	v_cvt_pk_bf16_f32 v220, v220, v221
	v_cvt_pk_bf16_f32 v221, v222, v223
	global_store_dwordx2 v164, v[220:221], s[50:51] offset:352
	v_mov_b32_e32 v167, v171
	s_nop 1
	v_permlane32_swap_b32_e32 v171, v167
	v_add_f32_e32 v171, v171, v167
	ds_swizzle_b32 v167, v171 offset:0x401f
	s_waitcnt lgkmcnt(0)
	v_add_f32_e32 v171, v171, v167
	v_cmp_gt_u32_e32 vcc, 16, v160
	s_and_saveexec_b64 s[98:99], vcc
	global_store_dword v166, v171, s[14:15] offset:3080
	s_or_b64 exec, exec, s[98:99]
	v_subrev_u32_e32 v164, 0x18000, v164
	s_branch .Lffn2_edone
; DI u32x4 pack8(const float (&v)[8]) { u32x4 r = {pk2(v[0], v[1]), pk2(v[2], v[3]), pk2(v[4], v[5]), pk2(v[6], v[7])}; return r; }
; DI void tile_ffn2(const Params& p, int l, const Chunk& ck, int tile, int next, PF& pf, char* smem) {
;     ...
;   float* xd = p.out + (size_t)(ck.tok0 + m0 + row) * 1024 + n0 + half * 64;
;   u16* xb = (u16*)(p.ws + OFF_XB) + (size_t)(m0 + row) * 1024 + n0 + half * 64;
; #pragma unroll
;   for (int c8 = 0; c8 < 8; ++c8) {
;     float v[8], x[8]; cs_ld8(Cs, row, half * 64 + c8 * 8, v); unpack8(*(const u32x4*)(xb + c8 * 8), x);
; #pragma unroll
;     for (int j = 0; j < 8; ++j) { v[j] += x[j]; ssq += v[j] * v[j]; }
;     if (l == 0) *(u32x4*)(xb + c8 * 8) = pack8(v);
;     else { *(f32x4*)(xd + c8 * 8) = f32x4{v[0], v[1], v[2], v[3]}; *(f32x4*)(xd + c8 * 8 + 4) = f32x4{v[4], v[5], v[6], v[7]}; }
.Lffn2_l1:
	global_load_dwordx2 v[224:225], v164, s[50:51] offset:0
	global_load_dwordx2 v[226:227], v164, s[50:51] offset:32
	global_load_dwordx2 v[228:229], v164, s[50:51] offset:64
	global_load_dwordx2 v[230:231], v164, s[50:51] offset:96
	v_add_u32_e32 v164, 0x8000, v164
	global_load_dwordx2 v[232:233], v164, s[50:51] offset:0
	global_load_dwordx2 v[234:235], v164, s[50:51] offset:32
	global_load_dwordx2 v[236:237], v164, s[50:51] offset:64
	global_load_dwordx2 v[238:239], v164, s[50:51] offset:96
	v_add_u32_e32 v164, 0x8000, v164
	global_load_dwordx2 v[240:241], v164, s[50:51] offset:0
	global_load_dwordx2 v[242:243], v164, s[50:51] offset:32
	global_load_dwordx2 v[244:245], v164, s[50:51] offset:64
	global_load_dwordx2 v[246:247], v164, s[50:51] offset:96
	v_add_u32_e32 v164, 0x8000, v164
	global_load_dwordx2 v[248:249], v164, s[50:51] offset:0
	global_load_dwordx2 v[250:251], v164, s[50:51] offset:32
	global_load_dwordx2 v[156:157], v164, s[50:51] offset:64
	global_load_dwordx2 v[158:159], v164, s[50:51] offset:96
	v_subrev_u32_e32 v164, 0x18000, v164
	s_waitcnt vmcnt(0)
	v_lshlrev_b32_e32 v167, 16, v224
	v_and_b32_e32 v168, 0xffff0000, v224
	v_lshlrev_b32_e32 v169, 16, v225
	v_and_b32_e32 v170, 0xffff0000, v225
	v_add_f32_e32 v2, v2, v167
	v_add_f32_e32 v3, v3, v168
	v_add_f32_e32 v4, v4, v169
	v_add_f32_e32 v5, v5, v170
	global_store_dwordx4 v165, v[2:5], s[12:13]
	v_lshlrev_b32_e32 v167, 16, v226
	v_and_b32_e32 v168, 0xffff0000, v226
	v_lshlrev_b32_e32 v169, 16, v227
	v_and_b32_e32 v170, 0xffff0000, v227
	v_add_f32_e32 v6, v6, v167
	v_add_f32_e32 v7, v7, v168
	v_add_f32_e32 v8, v8, v169
	v_add_f32_e32 v9, v9, v170
	global_store_dwordx4 v165, v[6:9], s[12:13] offset:64
	v_lshlrev_b32_e32 v167, 16, v228
	v_and_b32_e32 v168, 0xffff0000, v228
	v_lshlrev_b32_e32 v169, 16, v229
	v_and_b32_e32 v170, 0xffff0000, v229
	v_add_f32_e32 v10, v10, v167
	v_add_f32_e32 v11, v11, v168
	v_add_f32_e32 v12, v12, v169
	v_add_f32_e32 v13, v13, v170
	global_store_dwordx4 v165, v[10:13], s[12:13] offset:128
	v_lshlrev_b32_e32 v167, 16, v230
	v_and_b32_e32 v168, 0xffff0000, v230
	v_lshlrev_b32_e32 v169, 16, v231
	v_and_b32_e32 v170, 0xffff0000, v231
	v_add_f32_e32 v14, v14, v167
	v_add_f32_e32 v15, v15, v168
	v_add_f32_e32 v16, v16, v169
	v_add_f32_e32 v17, v17, v170
	global_store_dwordx4 v165, v[14:17], s[12:13] offset:192
	v_add_u32_e32 v165, 0x10000, v165
	v_lshlrev_b32_e32 v167, 16, v232
	v_and_b32_e32 v168, 0xffff0000, v232
	v_lshlrev_b32_e32 v169, 16, v233
	v_and_b32_e32 v170, 0xffff0000, v233
	v_add_f32_e32 v18, v18, v167
	v_add_f32_e32 v19, v19, v168
	v_add_f32_e32 v20, v20, v169
	v_add_f32_e32 v21, v21, v170
	global_store_dwordx4 v165, v[18:21], s[12:13]
	v_lshlrev_b32_e32 v167, 16, v234
	v_and_b32_e32 v168, 0xffff0000, v234
	v_lshlrev_b32_e32 v169, 16, v235
	v_and_b32_e32 v170, 0xffff0000, v235
	v_add_f32_e32 v22, v22, v167
	v_add_f32_e32 v23, v23, v168
	v_add_f32_e32 v24, v24, v169
	v_add_f32_e32 v25, v25, v170
	global_store_dwordx4 v165, v[22:25], s[12:13] offset:64
	v_lshlrev_b32_e32 v167, 16, v236
	v_and_b32_e32 v168, 0xffff0000, v236
	v_lshlrev_b32_e32 v169, 16, v237
	v_and_b32_e32 v170, 0xffff0000, v237
	v_add_f32_e32 v26, v26, v167
	v_add_f32_e32 v27, v27, v168
	v_add_f32_e32 v28, v28, v169
	v_add_f32_e32 v29, v29, v170
	global_store_dwordx4 v165, v[26:29], s[12:13] offset:128
	v_lshlrev_b32_e32 v167, 16, v238
	v_and_b32_e32 v168, 0xffff0000, v238
	v_lshlrev_b32_e32 v169, 16, v239
	v_and_b32_e32 v170, 0xffff0000, v239
	v_add_f32_e32 v30, v30, v167
	v_add_f32_e32 v31, v31, v168
	v_add_f32_e32 v32, v32, v169
	v_add_f32_e32 v33, v33, v170
	global_store_dwordx4 v165, v[30:33], s[12:13] offset:192
	v_add_u32_e32 v165, 0x10000, v165
	v_lshlrev_b32_e32 v167, 16, v240
	v_and_b32_e32 v168, 0xffff0000, v240
	v_lshlrev_b32_e32 v169, 16, v241
	v_and_b32_e32 v170, 0xffff0000, v241
	v_add_f32_e32 v34, v34, v167
	v_add_f32_e32 v35, v35, v168
	v_add_f32_e32 v36, v36, v169
	v_add_f32_e32 v37, v37, v170
	global_store_dwordx4 v165, v[34:37], s[12:13]
	v_lshlrev_b32_e32 v167, 16, v242
	v_and_b32_e32 v168, 0xffff0000, v242
	v_lshlrev_b32_e32 v169, 16, v243
	v_and_b32_e32 v170, 0xffff0000, v243
	v_add_f32_e32 v38, v38, v167
	v_add_f32_e32 v39, v39, v168
	v_add_f32_e32 v40, v40, v169
	v_add_f32_e32 v41, v41, v170
	global_store_dwordx4 v165, v[38:41], s[12:13] offset:64
	v_lshlrev_b32_e32 v167, 16, v244
	v_and_b32_e32 v168, 0xffff0000, v244
	v_lshlrev_b32_e32 v169, 16, v245
	v_and_b32_e32 v170, 0xffff0000, v245
	v_add_f32_e32 v42, v42, v167
	v_add_f32_e32 v43, v43, v168
	v_add_f32_e32 v44, v44, v169
	v_add_f32_e32 v45, v45, v170
	global_store_dwordx4 v165, v[42:45], s[12:13] offset:128
	v_lshlrev_b32_e32 v167, 16, v246
	v_and_b32_e32 v168, 0xffff0000, v246
	v_lshlrev_b32_e32 v169, 16, v247
	v_and_b32_e32 v170, 0xffff0000, v247
	v_add_f32_e32 v46, v46, v167
	v_add_f32_e32 v47, v47, v168
	v_add_f32_e32 v48, v48, v169
	v_add_f32_e32 v49, v49, v170
	global_store_dwordx4 v165, v[46:49], s[12:13] offset:192
	v_add_u32_e32 v165, 0x10000, v165
	v_lshlrev_b32_e32 v167, 16, v248
	v_and_b32_e32 v168, 0xffff0000, v248
	v_lshlrev_b32_e32 v169, 16, v249
	v_and_b32_e32 v170, 0xffff0000, v249
	v_add_f32_e32 v50, v50, v167
	v_add_f32_e32 v51, v51, v168
	v_add_f32_e32 v52, v52, v169
	v_add_f32_e32 v53, v53, v170
	global_store_dwordx4 v165, v[50:53], s[12:13]
	v_lshlrev_b32_e32 v167, 16, v250
	v_and_b32_e32 v168, 0xffff0000, v250
	v_lshlrev_b32_e32 v169, 16, v251
	v_and_b32_e32 v170, 0xffff0000, v251
	v_add_f32_e32 v54, v54, v167
	v_add_f32_e32 v55, v55, v168
	v_add_f32_e32 v56, v56, v169
	v_add_f32_e32 v57, v57, v170
	global_store_dwordx4 v165, v[54:57], s[12:13] offset:64
; DI u32x4 pack8(const float (&v)[8]) { u32x4 r = {pk2(v[0], v[1]), pk2(v[2], v[3]), pk2(v[4], v[5]), pk2(v[6], v[7])}; return r; }
; DI void tile_ffn2(const Params& p, int l, const Chunk& ck, int tile, int next, PF& pf, char* smem) {
;     ...
;   float* xd = p.out + (size_t)(ck.tok0 + m0 + row) * 1024 + n0 + half * 64;
;   u16* xb = (u16*)(p.ws + OFF_XB) + (size_t)(m0 + row) * 1024 + n0 + half * 64;
; #pragma unroll
;   for (int c8 = 0; c8 < 8; ++c8) {
;     float v[8], x[8]; cs_ld8(Cs, row, half * 64 + c8 * 8, v); unpack8(*(const u32x4*)(xb + c8 * 8), x);
; #pragma unroll
;     for (int j = 0; j < 8; ++j) { v[j] += x[j]; ssq += v[j] * v[j]; }
;     if (l == 0) *(u32x4*)(xb + c8 * 8) = pack8(v);
;     else { *(f32x4*)(xd + c8 * 8) = f32x4{v[0], v[1], v[2], v[3]}; *(f32x4*)(xd + c8 * 8 + 4) = f32x4{v[4], v[5], v[6], v[7]}; }
	v_lshlrev_b32_e32 v167, 16, v156
	v_and_b32_e32 v168, 0xffff0000, v156
	v_lshlrev_b32_e32 v169, 16, v157
	v_and_b32_e32 v170, 0xffff0000, v157
	v_add_f32_e32 v58, v58, v167
	v_add_f32_e32 v59, v59, v168
	v_add_f32_e32 v60, v60, v169
	v_add_f32_e32 v61, v61, v170
	global_store_dwordx4 v165, v[58:61], s[12:13] offset:128
	v_lshlrev_b32_e32 v167, 16, v158
	v_and_b32_e32 v168, 0xffff0000, v158
	v_lshlrev_b32_e32 v169, 16, v159
	v_and_b32_e32 v170, 0xffff0000, v159
	v_add_f32_e32 v62, v62, v167
	v_add_f32_e32 v63, v63, v168
	v_add_f32_e32 v64, v64, v169
	v_add_f32_e32 v65, v65, v170
	global_store_dwordx4 v165, v[62:65], s[12:13] offset:192
	v_subrev_u32_e32 v165, 0x30000, v165
	global_load_dwordx2 v[224:225], v164, s[50:51] offset:256
	global_load_dwordx2 v[226:227], v164, s[50:51] offset:288
	global_load_dwordx2 v[228:229], v164, s[50:51] offset:320
	global_load_dwordx2 v[230:231], v164, s[50:51] offset:352
	v_add_u32_e32 v164, 0x8000, v164
	global_load_dwordx2 v[232:233], v164, s[50:51] offset:256
	global_load_dwordx2 v[234:235], v164, s[50:51] offset:288
	global_load_dwordx2 v[236:237], v164, s[50:51] offset:320
	global_load_dwordx2 v[238:239], v164, s[50:51] offset:352
	v_add_u32_e32 v164, 0x8000, v164
	global_load_dwordx2 v[240:241], v164, s[50:51] offset:256
	global_load_dwordx2 v[242:243], v164, s[50:51] offset:288
	global_load_dwordx2 v[244:245], v164, s[50:51] offset:320
	global_load_dwordx2 v[246:247], v164, s[50:51] offset:352
	v_add_u32_e32 v164, 0x8000, v164
	global_load_dwordx2 v[248:249], v164, s[50:51] offset:256
	global_load_dwordx2 v[250:251], v164, s[50:51] offset:288
	global_load_dwordx2 v[156:157], v164, s[50:51] offset:320
	global_load_dwordx2 v[158:159], v164, s[50:51] offset:352
	v_subrev_u32_e32 v164, 0x18000, v164
	s_waitcnt vmcnt(0)
; DI u32x4 pack8(const float (&v)[8]) { u32x4 r = {pk2(v[0], v[1]), pk2(v[2], v[3]), pk2(v[4], v[5]), pk2(v[6], v[7])}; return r; }
; DI void tile_ffn2(const Params& p, int l, const Chunk& ck, int tile, int next, PF& pf, char* smem) {
;     ...
;   float* xd = p.out + (size_t)(ck.tok0 + m0 + row) * 1024 + n0 + half * 64;
;   u16* xb = (u16*)(p.ws + OFF_XB) + (size_t)(m0 + row) * 1024 + n0 + half * 64;
; #pragma unroll
;   for (int c8 = 0; c8 < 8; ++c8) {
;     float v[8], x[8]; cs_ld8(Cs, row, half * 64 + c8 * 8, v); unpack8(*(const u32x4*)(xb + c8 * 8), x);
; #pragma unroll
;     for (int j = 0; j < 8; ++j) { v[j] += x[j]; ssq += v[j] * v[j]; }
;     if (l == 0) *(u32x4*)(xb + c8 * 8) = pack8(v);
;     else { *(f32x4*)(xd + c8 * 8) = f32x4{v[0], v[1], v[2], v[3]}; *(f32x4*)(xd + c8 * 8 + 4) = f32x4{v[4], v[5], v[6], v[7]}; }
	v_lshlrev_b32_e32 v167, 16, v224
	v_and_b32_e32 v168, 0xffff0000, v224
	v_lshlrev_b32_e32 v169, 16, v225
	v_and_b32_e32 v170, 0xffff0000, v225
	v_add_f32_e32 v74, v74, v167
	v_add_f32_e32 v75, v75, v168
	v_add_f32_e32 v76, v76, v169
	v_add_f32_e32 v77, v77, v170
	global_store_dwordx4 v165, v[74:77], s[12:13] offset:512
	v_lshlrev_b32_e32 v167, 16, v226
	v_and_b32_e32 v168, 0xffff0000, v226
	v_lshlrev_b32_e32 v169, 16, v227
	v_and_b32_e32 v170, 0xffff0000, v227
	v_add_f32_e32 v78, v78, v167
	v_add_f32_e32 v79, v79, v168
	v_add_f32_e32 v80, v80, v169
	v_add_f32_e32 v81, v81, v170
	global_store_dwordx4 v165, v[78:81], s[12:13] offset:576
	v_lshlrev_b32_e32 v167, 16, v228
	v_and_b32_e32 v168, 0xffff0000, v228
	v_lshlrev_b32_e32 v169, 16, v229
	v_and_b32_e32 v170, 0xffff0000, v229
	v_add_f32_e32 v82, v82, v167
	v_add_f32_e32 v83, v83, v168
	v_add_f32_e32 v84, v84, v169
	v_add_f32_e32 v85, v85, v170
	global_store_dwordx4 v165, v[82:85], s[12:13] offset:640
	v_lshlrev_b32_e32 v167, 16, v230
	v_and_b32_e32 v168, 0xffff0000, v230
	v_lshlrev_b32_e32 v169, 16, v231
	v_and_b32_e32 v170, 0xffff0000, v231
	v_add_f32_e32 v86, v86, v167
	v_add_f32_e32 v87, v87, v168
	v_add_f32_e32 v88, v88, v169
	v_add_f32_e32 v89, v89, v170
	global_store_dwordx4 v165, v[86:89], s[12:13] offset:704
	v_add_u32_e32 v165, 0x10000, v165
	v_lshlrev_b32_e32 v167, 16, v232
	v_and_b32_e32 v168, 0xffff0000, v232
	v_lshlrev_b32_e32 v169, 16, v233
	v_and_b32_e32 v170, 0xffff0000, v233
	v_add_f32_e32 v90, v90, v167
	v_add_f32_e32 v91, v91, v168
	v_add_f32_e32 v92, v92, v169
	v_add_f32_e32 v93, v93, v170
	global_store_dwordx4 v165, v[90:93], s[12:13] offset:512
	v_lshlrev_b32_e32 v167, 16, v234
	v_and_b32_e32 v168, 0xffff0000, v234
	v_lshlrev_b32_e32 v169, 16, v235
	v_and_b32_e32 v170, 0xffff0000, v235
	v_add_f32_e32 v94, v94, v167
	v_add_f32_e32 v95, v95, v168
	v_add_f32_e32 v96, v96, v169
	v_add_f32_e32 v97, v97, v170
	global_store_dwordx4 v165, v[94:97], s[12:13] offset:576
	v_lshlrev_b32_e32 v167, 16, v236
	v_and_b32_e32 v168, 0xffff0000, v236
	v_lshlrev_b32_e32 v169, 16, v237
	v_and_b32_e32 v170, 0xffff0000, v237
	v_add_f32_e32 v98, v98, v167
	v_add_f32_e32 v99, v99, v168
	v_add_f32_e32 v100, v100, v169
	v_add_f32_e32 v101, v101, v170
	global_store_dwordx4 v165, v[98:101], s[12:13] offset:640
	v_lshlrev_b32_e32 v167, 16, v238
	v_and_b32_e32 v168, 0xffff0000, v238
	v_lshlrev_b32_e32 v169, 16, v239
	v_and_b32_e32 v170, 0xffff0000, v239
	v_add_f32_e32 v102, v102, v167
	v_add_f32_e32 v103, v103, v168
	v_add_f32_e32 v104, v104, v169
	v_add_f32_e32 v105, v105, v170
	global_store_dwordx4 v165, v[102:105], s[12:13] offset:704
	v_add_u32_e32 v165, 0x10000, v165
	v_lshlrev_b32_e32 v167, 16, v240
	v_and_b32_e32 v168, 0xffff0000, v240
	v_lshlrev_b32_e32 v169, 16, v241
	v_and_b32_e32 v170, 0xffff0000, v241
	v_add_f32_e32 v106, v106, v167
	v_add_f32_e32 v107, v107, v168
	v_add_f32_e32 v108, v108, v169
	v_add_f32_e32 v109, v109, v170
	global_store_dwordx4 v165, v[106:109], s[12:13] offset:512
	v_lshlrev_b32_e32 v167, 16, v242
	v_and_b32_e32 v168, 0xffff0000, v242
	v_lshlrev_b32_e32 v169, 16, v243
	v_and_b32_e32 v170, 0xffff0000, v243
	v_add_f32_e32 v110, v110, v167
	v_add_f32_e32 v111, v111, v168
	v_add_f32_e32 v112, v112, v169
	v_add_f32_e32 v113, v113, v170
	global_store_dwordx4 v165, v[110:113], s[12:13] offset:576
	v_lshlrev_b32_e32 v167, 16, v244
	v_and_b32_e32 v168, 0xffff0000, v244
	v_lshlrev_b32_e32 v169, 16, v245
	v_and_b32_e32 v170, 0xffff0000, v245
	v_add_f32_e32 v114, v114, v167
	v_add_f32_e32 v115, v115, v168
	v_add_f32_e32 v116, v116, v169
	v_add_f32_e32 v117, v117, v170
	global_store_dwordx4 v165, v[114:117], s[12:13] offset:640
	v_lshlrev_b32_e32 v167, 16, v246
	v_and_b32_e32 v168, 0xffff0000, v246
	v_lshlrev_b32_e32 v169, 16, v247
	v_and_b32_e32 v170, 0xffff0000, v247
	v_add_f32_e32 v118, v118, v167
	v_add_f32_e32 v119, v119, v168
	v_add_f32_e32 v120, v120, v169
	v_add_f32_e32 v121, v121, v170
	global_store_dwordx4 v165, v[118:121], s[12:13] offset:704
	v_add_u32_e32 v165, 0x10000, v165
	v_lshlrev_b32_e32 v167, 16, v248
	v_and_b32_e32 v168, 0xffff0000, v248
	v_lshlrev_b32_e32 v169, 16, v249
	v_and_b32_e32 v170, 0xffff0000, v249
	v_add_f32_e32 v208, v208, v167
	v_add_f32_e32 v209, v209, v168
	v_add_f32_e32 v210, v210, v169
	v_add_f32_e32 v211, v211, v170
	global_store_dwordx4 v165, v[208:211], s[12:13] offset:512
	v_lshlrev_b32_e32 v167, 16, v250
	v_and_b32_e32 v168, 0xffff0000, v250
	v_lshlrev_b32_e32 v169, 16, v251
	v_and_b32_e32 v170, 0xffff0000, v251
	v_add_f32_e32 v212, v212, v167
	v_add_f32_e32 v213, v213, v168
	v_add_f32_e32 v214, v214, v169
	v_add_f32_e32 v215, v215, v170
	global_store_dwordx4 v165, v[212:215], s[12:13] offset:576
	v_lshlrev_b32_e32 v167, 16, v156
	v_and_b32_e32 v168, 0xffff0000, v156
	v_lshlrev_b32_e32 v169, 16, v157
	v_and_b32_e32 v170, 0xffff0000, v157
	v_add_f32_e32 v216, v216, v167
	v_add_f32_e32 v217, v217, v168
	v_add_f32_e32 v218, v218, v169
	v_add_f32_e32 v219, v219, v170
	global_store_dwordx4 v165, v[216:219], s[12:13] offset:640
	v_lshlrev_b32_e32 v167, 16, v158
	v_and_b32_e32 v168, 0xffff0000, v158
	v_lshlrev_b32_e32 v169, 16, v159
	v_and_b32_e32 v170, 0xffff0000, v159
	v_add_f32_e32 v220, v220, v167
	v_add_f32_e32 v221, v221, v168
	v_add_f32_e32 v222, v222, v169
	v_add_f32_e32 v223, v223, v170
	global_store_dwordx4 v165, v[220:223], s[12:13] offset:704
	v_subrev_u32_e32 v165, 0x30000, v165
.Lffn2_edone:
	s_branch .LBB1_205
.LBB1_241:
	s_mov_b64 s[22:23], 0

; DI void st8(u16* dst, const float (&v)[8]) { *(u32x4*)dst = pack8(v); }
; DI void tile_ffn1(const Params& p, int l, const Chunk& ck, int tile, int next, PF& pf, char* smem) {
;     ...
;   rowss_finish(rss, rinv_s);
;   acc_to_cs(acc, Cs);
;   const int row = tid >> 1, half = tid & 1; const float rinv = rinv_s[row]; float v[8];
;   u16* dst = (u16*)(p.ws + OFF_H) + (size_t)(m0 + row) * 4096 + n0 + half * 64;
; #pragma unroll
;   for (int c8 = 0; c8 < 8; ++c8) { cs_ld8(Cs, row, half * 64 + c8 * 8, v);
; #pragma unroll
;     for (int j = 0; j < 8; ++j) { const float r = fmaxf(v[j] * rinv, 0.f); v[j] = r * r; }
;     st8(dst + c8 * 8, v); }
.LBB1_245:
	s_or_b64 exec, exec, s[28:29]
	s_waitcnt lgkmcnt(0)
	s_barrier
	v_and_b32_e32 v208, 63, v172
	v_lshrrev_b32_e32 v209, 6, v172
	v_and_b32_e32 v210, 15, v208
	v_lshrrev_b32_e32 v211, 1, v209
	v_lshl_add_u32 v210, v211, 6, v210
	v_lshlrev_b32_e32 v212, 2, v210
	v_add_u32_e32 v212, 0x12000, v212
	ds_read_b32 v213, v212 offset:0
	ds_read_b32 v214, v212 offset:64
	ds_read_b32 v215, v212 offset:128
	ds_read_b32 v216, v212 offset:192
	v_add_u32_e32 v210, s41, v210
	v_lshlrev_b32_e32 v210, 6, v210
	v_lshrrev_b32_e32 v211, 4, v208
	v_lshl_add_u32 v210, v211, 3, v210
	v_and_b32_e32 v211, 1, v209
	v_lshlrev_b32_e32 v211, 21, v211
	s_lshl_b32 s0, s26, 15
	v_add3_u32 v210, v210, v211, s0
	s_waitcnt lgkmcnt(0)
	v_mul_f32_e32 v2, v213, v2
	v_mul_f32_e32 v3, v213, v3
	v_mul_f32_e32 v4, v213, v4
	v_mul_f32_e32 v5, v213, v5
	v_max_f32_e32 v2, 0, v2
	v_max_f32_e32 v3, 0, v3
	v_max_f32_e32 v4, 0, v4
	v_max_f32_e32 v5, 0, v5
	v_mul_f32_e32 v2, v2, v2
	v_mul_f32_e32 v3, v3, v3
	v_mul_f32_e32 v4, v4, v4
	v_mul_f32_e32 v5, v5, v5
	v_cvt_pk_bf16_f32 v2, v2, v3
	v_cvt_pk_bf16_f32 v3, v4, v5
	global_store_dwordx2 v210, v[2:3], s[22:23]
	v_mul_f32_e32 v18, v214, v18
	v_mul_f32_e32 v19, v214, v19
	v_mul_f32_e32 v20, v214, v20
	v_mul_f32_e32 v21, v214, v21
	v_max_f32_e32 v18, 0, v18
	v_max_f32_e32 v19, 0, v19
	v_max_f32_e32 v20, 0, v20
	v_max_f32_e32 v21, 0, v21
	v_mul_f32_e32 v18, v18, v18
	v_mul_f32_e32 v19, v19, v19
	v_mul_f32_e32 v20, v20, v20
	v_mul_f32_e32 v21, v21, v21
	v_cvt_pk_bf16_f32 v18, v18, v19
	v_cvt_pk_bf16_f32 v19, v20, v21
	global_store_dwordx2 v210, v[18:19], s[22:23] offset:1024
	v_mul_f32_e32 v34, v215, v34
	v_mul_f32_e32 v35, v215, v35
	v_mul_f32_e32 v36, v215, v36
	v_mul_f32_e32 v37, v215, v37
	v_max_f32_e32 v34, 0, v34
	v_max_f32_e32 v35, 0, v35
	v_max_f32_e32 v36, 0, v36
	v_max_f32_e32 v37, 0, v37
	v_mul_f32_e32 v34, v34, v34
	v_mul_f32_e32 v35, v35, v35
	v_mul_f32_e32 v36, v36, v36
	v_mul_f32_e32 v37, v37, v37
	v_cvt_pk_bf16_f32 v34, v34, v35
	v_cvt_pk_bf16_f32 v35, v36, v37
	global_store_dwordx2 v210, v[34:35], s[22:23] offset:2048
	v_mul_f32_e32 v50, v216, v50
	v_mul_f32_e32 v51, v216, v51
	v_mul_f32_e32 v52, v216, v52
	v_mul_f32_e32 v53, v216, v53
	v_max_f32_e32 v50, 0, v50
	v_max_f32_e32 v51, 0, v51
	v_max_f32_e32 v52, 0, v52
	v_max_f32_e32 v53, 0, v53
	v_mul_f32_e32 v50, v50, v50
	v_mul_f32_e32 v51, v51, v51
	v_mul_f32_e32 v52, v52, v52
	v_mul_f32_e32 v53, v53, v53
	v_cvt_pk_bf16_f32 v50, v50, v51
	v_cvt_pk_bf16_f32 v51, v52, v53
	global_store_dwordx2 v210, v[50:51], s[22:23] offset:3072
	v_mul_f32_e32 v6, v213, v6
	v_mul_f32_e32 v7, v213, v7
	v_mul_f32_e32 v8, v213, v8
	v_mul_f32_e32 v9, v213, v9
	v_max_f32_e32 v6, 0, v6
	v_max_f32_e32 v7, 0, v7
	v_max_f32_e32 v8, 0, v8
	v_max_f32_e32 v9, 0, v9
	v_mul_f32_e32 v6, v6, v6
	v_mul_f32_e32 v7, v7, v7
	v_mul_f32_e32 v8, v8, v8
	v_mul_f32_e32 v9, v9, v9
	v_cvt_pk_bf16_f32 v6, v6, v7
	v_cvt_pk_bf16_f32 v7, v8, v9
	global_store_dwordx2 v210, v[6:7], s[22:23] offset:32
	v_mul_f32_e32 v22, v214, v22
	v_mul_f32_e32 v23, v214, v23
	v_mul_f32_e32 v24, v214, v24
	v_mul_f32_e32 v25, v214, v25
	v_max_f32_e32 v22, 0, v22
	v_max_f32_e32 v23, 0, v23
	v_max_f32_e32 v24, 0, v24
	v_max_f32_e32 v25, 0, v25
	v_mul_f32_e32 v22, v22, v22
	v_mul_f32_e32 v23, v23, v23
	v_mul_f32_e32 v24, v24, v24
	v_mul_f32_e32 v25, v25, v25
	v_cvt_pk_bf16_f32 v22, v22, v23
	v_cvt_pk_bf16_f32 v23, v24, v25
	global_store_dwordx2 v210, v[22:23], s[22:23] offset:1056
	v_mul_f32_e32 v38, v215, v38
	v_mul_f32_e32 v39, v215, v39
	v_mul_f32_e32 v40, v215, v40
	v_mul_f32_e32 v41, v215, v41
	v_max_f32_e32 v38, 0, v38
	v_max_f32_e32 v39, 0, v39
	v_max_f32_e32 v40, 0, v40
	v_max_f32_e32 v41, 0, v41
	v_mul_f32_e32 v38, v38, v38
	v_mul_f32_e32 v39, v39, v39
	v_mul_f32_e32 v40, v40, v40
	v_mul_f32_e32 v41, v41, v41
	v_cvt_pk_bf16_f32 v38, v38, v39
	v_cvt_pk_bf16_f32 v39, v40, v41
	global_store_dwordx2 v210, v[38:39], s[22:23] offset:2080
	v_mul_f32_e32 v54, v216, v54
	v_mul_f32_e32 v55, v216, v55
	v_mul_f32_e32 v56, v216, v56
	v_mul_f32_e32 v57, v216, v57
	v_max_f32_e32 v54, 0, v54
	v_max_f32_e32 v55, 0, v55
	v_max_f32_e32 v56, 0, v56
	v_max_f32_e32 v57, 0, v57
	v_mul_f32_e32 v54, v54, v54
	v_mul_f32_e32 v55, v55, v55
	v_mul_f32_e32 v56, v56, v56
	v_mul_f32_e32 v57, v57, v57
	v_cvt_pk_bf16_f32 v54, v54, v55
	v_cvt_pk_bf16_f32 v55, v56, v57
	global_store_dwordx2 v210, v[54:55], s[22:23] offset:3104
	v_add_u32_e32 v210, 0x100000, v210
	v_mul_f32_e32 v10, v213, v10
	v_mul_f32_e32 v11, v213, v11
	v_mul_f32_e32 v12, v213, v12
	v_mul_f32_e32 v13, v213, v13
	v_max_f32_e32 v10, 0, v10
	v_max_f32_e32 v11, 0, v11
	v_max_f32_e32 v12, 0, v12
	v_max_f32_e32 v13, 0, v13
	v_mul_f32_e32 v10, v10, v10
	v_mul_f32_e32 v11, v11, v11
	v_mul_f32_e32 v12, v12, v12
	v_mul_f32_e32 v13, v13, v13
	v_cvt_pk_bf16_f32 v10, v10, v11
	v_cvt_pk_bf16_f32 v11, v12, v13
	global_store_dwordx2 v210, v[10:11], s[22:23]
	v_mul_f32_e32 v26, v214, v26
	v_mul_f32_e32 v27, v214, v27
	v_mul_f32_e32 v28, v214, v28
	v_mul_f32_e32 v29, v214, v29
	v_max_f32_e32 v26, 0, v26
	v_max_f32_e32 v27, 0, v27
	v_max_f32_e32 v28, 0, v28
	v_max_f32_e32 v29, 0, v29
	v_mul_f32_e32 v26, v26, v26
	v_mul_f32_e32 v27, v27, v27
	v_mul_f32_e32 v28, v28, v28
	v_mul_f32_e32 v29, v29, v29
	v_cvt_pk_bf16_f32 v26, v26, v27
	v_cvt_pk_bf16_f32 v27, v28, v29
	global_store_dwordx2 v210, v[26:27], s[22:23] offset:1024
	v_mul_f32_e32 v42, v215, v42
	v_mul_f32_e32 v43, v215, v43
	v_mul_f32_e32 v44, v215, v44
	v_mul_f32_e32 v45, v215, v45
	v_max_f32_e32 v42, 0, v42
	v_max_f32_e32 v43, 0, v43
	v_max_f32_e32 v44, 0, v44
	v_max_f32_e32 v45, 0, v45
	v_mul_f32_e32 v42, v42, v42
	v_mul_f32_e32 v43, v43, v43
; DI void st8(u16* dst, const float (&v)[8]) { *(u32x4*)dst = pack8(v); }
; DI void tile_ffn1(const Params& p, int l, const Chunk& ck, int tile, int next, PF& pf, char* smem) {
;     ...
;   const int row = tid >> 1, half = tid & 1; const float rinv = rinv_s[row]; float v[8];
;   u16* dst = (u16*)(p.ws + OFF_H) + (size_t)(m0 + row) * 4096 + n0 + half * 64;
; #pragma unroll
;   for (int c8 = 0; c8 < 8; ++c8) { cs_ld8(Cs, row, half * 64 + c8 * 8, v);
; #pragma unroll
;     for (int j = 0; j < 8; ++j) { const float r = fmaxf(v[j] * rinv, 0.f); v[j] = r * r; }
;     st8(dst + c8 * 8, v); }
	v_mul_f32_e32 v44, v44, v44
	v_mul_f32_e32 v45, v45, v45
	v_cvt_pk_bf16_f32 v42, v42, v43
	v_cvt_pk_bf16_f32 v43, v44, v45
	global_store_dwordx2 v210, v[42:43], s[22:23] offset:2048
	v_mul_f32_e32 v58, v216, v58
	v_mul_f32_e32 v59, v216, v59
	v_mul_f32_e32 v60, v216, v60
	v_mul_f32_e32 v61, v216, v61
	v_max_f32_e32 v58, 0, v58
	v_max_f32_e32 v59, 0, v59
	v_max_f32_e32 v60, 0, v60
	v_max_f32_e32 v61, 0, v61
	v_mul_f32_e32 v58, v58, v58
	v_mul_f32_e32 v59, v59, v59
	v_mul_f32_e32 v60, v60, v60
	v_mul_f32_e32 v61, v61, v61
	v_cvt_pk_bf16_f32 v58, v58, v59
	v_cvt_pk_bf16_f32 v59, v60, v61
	global_store_dwordx2 v210, v[58:59], s[22:23] offset:3072
	v_mul_f32_e32 v14, v213, v14
	v_mul_f32_e32 v15, v213, v15
	v_mul_f32_e32 v16, v213, v16
	v_mul_f32_e32 v17, v213, v17
	v_max_f32_e32 v14, 0, v14
	v_max_f32_e32 v15, 0, v15
	v_max_f32_e32 v16, 0, v16
	v_max_f32_e32 v17, 0, v17
	v_mul_f32_e32 v14, v14, v14
	v_mul_f32_e32 v15, v15, v15
	v_mul_f32_e32 v16, v16, v16
	v_mul_f32_e32 v17, v17, v17
	v_cvt_pk_bf16_f32 v14, v14, v15
	v_cvt_pk_bf16_f32 v15, v16, v17
	global_store_dwordx2 v210, v[14:15], s[22:23] offset:32
	v_mul_f32_e32 v30, v214, v30
	v_mul_f32_e32 v31, v214, v31
	v_mul_f32_e32 v32, v214, v32
	v_mul_f32_e32 v33, v214, v33
	v_max_f32_e32 v30, 0, v30
	v_max_f32_e32 v31, 0, v31
	v_max_f32_e32 v32, 0, v32
	v_max_f32_e32 v33, 0, v33
	v_mul_f32_e32 v30, v30, v30
	v_mul_f32_e32 v31, v31, v31
	v_mul_f32_e32 v32, v32, v32
	v_mul_f32_e32 v33, v33, v33
	v_cvt_pk_bf16_f32 v30, v30, v31
	v_cvt_pk_bf16_f32 v31, v32, v33
	global_store_dwordx2 v210, v[30:31], s[22:23] offset:1056
	v_mul_f32_e32 v46, v215, v46
	v_mul_f32_e32 v47, v215, v47
	v_mul_f32_e32 v48, v215, v48
	v_mul_f32_e32 v49, v215, v49
	v_max_f32_e32 v46, 0, v46
	v_max_f32_e32 v47, 0, v47
	v_max_f32_e32 v48, 0, v48
	v_max_f32_e32 v49, 0, v49
	v_mul_f32_e32 v46, v46, v46
	v_mul_f32_e32 v47, v47, v47
	v_mul_f32_e32 v48, v48, v48
	v_mul_f32_e32 v49, v49, v49
	v_cvt_pk_bf16_f32 v46, v46, v47
	v_cvt_pk_bf16_f32 v47, v48, v49
	global_store_dwordx2 v210, v[46:47], s[22:23] offset:2080
	v_mul_f32_e32 v62, v216, v62
	v_mul_f32_e32 v63, v216, v63
	v_mul_f32_e32 v64, v216, v64
	v_mul_f32_e32 v65, v216, v65
	v_max_f32_e32 v62, 0, v62
	v_max_f32_e32 v63, 0, v63
	v_max_f32_e32 v64, 0, v64
	v_max_f32_e32 v65, 0, v65
	v_mul_f32_e32 v62, v62, v62
	v_mul_f32_e32 v63, v63, v63
	v_mul_f32_e32 v64, v64, v64
	v_mul_f32_e32 v65, v65, v65
	v_cvt_pk_bf16_f32 v62, v62, v63
	v_cvt_pk_bf16_f32 v63, v64, v65
	global_store_dwordx2 v210, v[62:63], s[22:23] offset:3104
	v_add_u32_e32 v210, 0x300000, v210
	v_mul_f32_e32 v74, v213, v74
	v_mul_f32_e32 v75, v213, v75
	v_mul_f32_e32 v76, v213, v76
	v_mul_f32_e32 v77, v213, v77
	v_max_f32_e32 v74, 0, v74
	v_max_f32_e32 v75, 0, v75
	v_max_f32_e32 v76, 0, v76
	v_max_f32_e32 v77, 0, v77
	v_mul_f32_e32 v74, v74, v74
	v_mul_f32_e32 v75, v75, v75
	v_mul_f32_e32 v76, v76, v76
	v_mul_f32_e32 v77, v77, v77
	v_cvt_pk_bf16_f32 v74, v74, v75
	v_cvt_pk_bf16_f32 v75, v76, v77
	global_store_dwordx2 v210, v[74:75], s[22:23]
	v_mul_f32_e32 v90, v214, v90
	v_mul_f32_e32 v91, v214, v91
	v_mul_f32_e32 v92, v214, v92
	v_mul_f32_e32 v93, v214, v93
	v_max_f32_e32 v90, 0, v90
	v_max_f32_e32 v91, 0, v91
	v_max_f32_e32 v92, 0, v92
	v_max_f32_e32 v93, 0, v93
	v_mul_f32_e32 v90, v90, v90
	v_mul_f32_e32 v91, v91, v91
	v_mul_f32_e32 v92, v92, v92
	v_mul_f32_e32 v93, v93, v93
	v_cvt_pk_bf16_f32 v90, v90, v91
	v_cvt_pk_bf16_f32 v91, v92, v93
	global_store_dwordx2 v210, v[90:91], s[22:23] offset:1024
	v_mul_f32_e32 v106, v215, v106
	v_mul_f32_e32 v107, v215, v107
	v_mul_f32_e32 v108, v215, v108
	v_mul_f32_e32 v109, v215, v109
	v_max_f32_e32 v106, 0, v106
	v_max_f32_e32 v107, 0, v107
	v_max_f32_e32 v108, 0, v108
	v_max_f32_e32 v109, 0, v109
	v_mul_f32_e32 v106, v106, v106
	v_mul_f32_e32 v107, v107, v107
	v_mul_f32_e32 v108, v108, v108
	v_mul_f32_e32 v109, v109, v109
	v_cvt_pk_bf16_f32 v106, v106, v107
	v_cvt_pk_bf16_f32 v107, v108, v109
	global_store_dwordx2 v210, v[106:107], s[22:23] offset:2048
	v_mul_f32_e32 v122, v216, v122
	v_mul_f32_e32 v123, v216, v123
	v_mul_f32_e32 v124, v216, v124
	v_mul_f32_e32 v125, v216, v125
	v_max_f32_e32 v122, 0, v122
	v_max_f32_e32 v123, 0, v123
	v_max_f32_e32 v124, 0, v124
	v_max_f32_e32 v125, 0, v125
	v_mul_f32_e32 v122, v122, v122
	v_mul_f32_e32 v123, v123, v123
	v_mul_f32_e32 v124, v124, v124
	v_mul_f32_e32 v125, v125, v125
	v_cvt_pk_bf16_f32 v122, v122, v123
	v_cvt_pk_bf16_f32 v123, v124, v125
	global_store_dwordx2 v210, v[122:123], s[22:23] offset:3072
	v_mul_f32_e32 v78, v213, v78
	v_mul_f32_e32 v79, v213, v79
	v_mul_f32_e32 v80, v213, v80
	v_mul_f32_e32 v81, v213, v81
	v_max_f32_e32 v78, 0, v78
	v_max_f32_e32 v79, 0, v79
	v_max_f32_e32 v80, 0, v80
	v_max_f32_e32 v81, 0, v81
	v_mul_f32_e32 v78, v78, v78
	v_mul_f32_e32 v79, v79, v79
	v_mul_f32_e32 v80, v80, v80
	v_mul_f32_e32 v81, v81, v81
	v_cvt_pk_bf16_f32 v78, v78, v79
	v_cvt_pk_bf16_f32 v79, v80, v81
	global_store_dwordx2 v210, v[78:79], s[22:23] offset:32
	v_mul_f32_e32 v94, v214, v94
	v_mul_f32_e32 v95, v214, v95
	v_mul_f32_e32 v96, v214, v96
	v_mul_f32_e32 v97, v214, v97
	v_max_f32_e32 v94, 0, v94
	v_max_f32_e32 v95, 0, v95
	v_max_f32_e32 v96, 0, v96
	v_max_f32_e32 v97, 0, v97
	v_mul_f32_e32 v94, v94, v94
	v_mul_f32_e32 v95, v95, v95
; DI void st8(u16* dst, const float (&v)[8]) { *(u32x4*)dst = pack8(v); }
; DI void tile_ffn1(const Params& p, int l, const Chunk& ck, int tile, int next, PF& pf, char* smem) {
;     ...
;   const int row = tid >> 1, half = tid & 1; const float rinv = rinv_s[row]; float v[8];
;   u16* dst = (u16*)(p.ws + OFF_H) + (size_t)(m0 + row) * 4096 + n0 + half * 64;
; #pragma unroll
;   for (int c8 = 0; c8 < 8; ++c8) { cs_ld8(Cs, row, half * 64 + c8 * 8, v);
; #pragma unroll
;     for (int j = 0; j < 8; ++j) { const float r = fmaxf(v[j] * rinv, 0.f); v[j] = r * r; }
;     st8(dst + c8 * 8, v); }
	v_mul_f32_e32 v96, v96, v96
	v_mul_f32_e32 v97, v97, v97
	v_cvt_pk_bf16_f32 v94, v94, v95
	v_cvt_pk_bf16_f32 v95, v96, v97
	global_store_dwordx2 v210, v[94:95], s[22:23] offset:1056
	v_mul_f32_e32 v110, v215, v110
	v_mul_f32_e32 v111, v215, v111
	v_mul_f32_e32 v112, v215, v112
	v_mul_f32_e32 v113, v215, v113
	v_max_f32_e32 v110, 0, v110
	v_max_f32_e32 v111, 0, v111
	v_max_f32_e32 v112, 0, v112
	v_max_f32_e32 v113, 0, v113
	v_mul_f32_e32 v110, v110, v110
	v_mul_f32_e32 v111, v111, v111
	v_mul_f32_e32 v112, v112, v112
	v_mul_f32_e32 v113, v113, v113
	v_cvt_pk_bf16_f32 v110, v110, v111
	v_cvt_pk_bf16_f32 v111, v112, v113
	global_store_dwordx2 v210, v[110:111], s[22:23] offset:2080
	v_mul_f32_e32 v126, v216, v126
	v_mul_f32_e32 v127, v216, v127
	v_mul_f32_e32 v128, v216, v128
	v_mul_f32_e32 v129, v216, v129
	v_max_f32_e32 v126, 0, v126
	v_max_f32_e32 v127, 0, v127
	v_max_f32_e32 v128, 0, v128
	v_max_f32_e32 v129, 0, v129
	v_mul_f32_e32 v126, v126, v126
	v_mul_f32_e32 v127, v127, v127
	v_mul_f32_e32 v128, v128, v128
	v_mul_f32_e32 v129, v129, v129
	v_cvt_pk_bf16_f32 v126, v126, v127
	v_cvt_pk_bf16_f32 v127, v128, v129
	global_store_dwordx2 v210, v[126:127], s[22:23] offset:3104
	v_add_u32_e32 v210, 0x100000, v210
	v_mul_f32_e32 v82, v213, v82
	v_mul_f32_e32 v83, v213, v83
	v_mul_f32_e32 v84, v213, v84
	v_mul_f32_e32 v85, v213, v85
	v_max_f32_e32 v82, 0, v82
	v_max_f32_e32 v83, 0, v83
	v_max_f32_e32 v84, 0, v84
	v_max_f32_e32 v85, 0, v85
	v_mul_f32_e32 v82, v82, v82
	v_mul_f32_e32 v83, v83, v83
	v_mul_f32_e32 v84, v84, v84
	v_mul_f32_e32 v85, v85, v85
	v_cvt_pk_bf16_f32 v82, v82, v83
	v_cvt_pk_bf16_f32 v83, v84, v85
	global_store_dwordx2 v210, v[82:83], s[22:23]
	v_mul_f32_e32 v98, v214, v98
	v_mul_f32_e32 v99, v214, v99
	v_mul_f32_e32 v100, v214, v100
	v_mul_f32_e32 v101, v214, v101
	v_max_f32_e32 v98, 0, v98
	v_max_f32_e32 v99, 0, v99
	v_max_f32_e32 v100, 0, v100
	v_max_f32_e32 v101, 0, v101
	v_mul_f32_e32 v98, v98, v98
	v_mul_f32_e32 v99, v99, v99
	v_mul_f32_e32 v100, v100, v100
	v_mul_f32_e32 v101, v101, v101
	v_cvt_pk_bf16_f32 v98, v98, v99
	v_cvt_pk_bf16_f32 v99, v100, v101
	global_store_dwordx2 v210, v[98:99], s[22:23] offset:1024
	v_mul_f32_e32 v114, v215, v114
	v_mul_f32_e32 v115, v215, v115
	v_mul_f32_e32 v116, v215, v116
	v_mul_f32_e32 v117, v215, v117
	v_max_f32_e32 v114, 0, v114
	v_max_f32_e32 v115, 0, v115
	v_max_f32_e32 v116, 0, v116
	v_max_f32_e32 v117, 0, v117
	v_mul_f32_e32 v114, v114, v114
	v_mul_f32_e32 v115, v115, v115
	v_mul_f32_e32 v116, v116, v116
	v_mul_f32_e32 v117, v117, v117
	v_cvt_pk_bf16_f32 v114, v114, v115
	v_cvt_pk_bf16_f32 v115, v116, v117
	global_store_dwordx2 v210, v[114:115], s[22:23] offset:2048
	v_mul_f32_e32 v130, v216, v130
	v_mul_f32_e32 v131, v216, v131
	v_mul_f32_e32 v132, v216, v132
	v_mul_f32_e32 v133, v216, v133
	v_max_f32_e32 v130, 0, v130
	v_max_f32_e32 v131, 0, v131
	v_max_f32_e32 v132, 0, v132
	v_max_f32_e32 v133, 0, v133
	v_mul_f32_e32 v130, v130, v130
	v_mul_f32_e32 v131, v131, v131
	v_mul_f32_e32 v132, v132, v132
	v_mul_f32_e32 v133, v133, v133
	v_cvt_pk_bf16_f32 v130, v130, v131
	v_cvt_pk_bf16_f32 v131, v132, v133
	global_store_dwordx2 v210, v[130:131], s[22:23] offset:3072
	v_mul_f32_e32 v86, v213, v86
	v_mul_f32_e32 v87, v213, v87
	v_mul_f32_e32 v88, v213, v88
	v_mul_f32_e32 v89, v213, v89
	v_max_f32_e32 v86, 0, v86
	v_max_f32_e32 v87, 0, v87
	v_max_f32_e32 v88, 0, v88
	v_max_f32_e32 v89, 0, v89
	v_mul_f32_e32 v86, v86, v86
	v_mul_f32_e32 v87, v87, v87
	v_mul_f32_e32 v88, v88, v88
	v_mul_f32_e32 v89, v89, v89
	v_cvt_pk_bf16_f32 v86, v86, v87
	v_cvt_pk_bf16_f32 v87, v88, v89
	global_store_dwordx2 v210, v[86:87], s[22:23] offset:32
	v_mul_f32_e32 v102, v214, v102
	v_mul_f32_e32 v103, v214, v103
	v_mul_f32_e32 v104, v214, v104
	v_mul_f32_e32 v105, v214, v105
	v_max_f32_e32 v102, 0, v102
	v_max_f32_e32 v103, 0, v103
	v_max_f32_e32 v104, 0, v104
	v_max_f32_e32 v105, 0, v105
	v_mul_f32_e32 v102, v102, v102
	v_mul_f32_e32 v103, v103, v103
	v_mul_f32_e32 v104, v104, v104
	v_mul_f32_e32 v105, v105, v105
	v_cvt_pk_bf16_f32 v102, v102, v103
	v_cvt_pk_bf16_f32 v103, v104, v105
	global_store_dwordx2 v210, v[102:103], s[22:23] offset:1056
	v_mul_f32_e32 v118, v215, v118
	v_mul_f32_e32 v119, v215, v119
	v_mul_f32_e32 v120, v215, v120
	v_mul_f32_e32 v121, v215, v121
	v_max_f32_e32 v118, 0, v118
	v_max_f32_e32 v119, 0, v119
	v_max_f32_e32 v120, 0, v120
	v_max_f32_e32 v121, 0, v121
	v_mul_f32_e32 v118, v118, v118
	v_mul_f32_e32 v119, v119, v119
	v_mul_f32_e32 v120, v120, v120
	v_mul_f32_e32 v121, v121, v121
	v_cvt_pk_bf16_f32 v118, v118, v119
	v_cvt_pk_bf16_f32 v119, v120, v121
	global_store_dwordx2 v210, v[118:119], s[22:23] offset:2080
	v_mul_f32_e32 v134, v216, v134
	v_mul_f32_e32 v135, v216, v135
	v_mul_f32_e32 v136, v216, v136
	v_mul_f32_e32 v137, v216, v137
	v_max_f32_e32 v134, 0, v134
	v_max_f32_e32 v135, 0, v135
	v_max_f32_e32 v136, 0, v136
	v_max_f32_e32 v137, 0, v137
	v_mul_f32_e32 v134, v134, v134
	v_mul_f32_e32 v135, v135, v135
	v_mul_f32_e32 v136, v136, v136
	v_mul_f32_e32 v137, v137, v137
	v_cvt_pk_bf16_f32 v134, v134, v135
	v_cvt_pk_bf16_f32 v135, v136, v137
	global_store_dwordx2 v210, v[134:135], s[22:23] offset:3104
	s_add_i32 s35, s35, s59
	s_add_i32 s40, s40, s95
	s_and_b64 vcc, exec, s[24:25]
	s_cbranch_vccnz .LBB1_250

; #define BLOAD(A_, B_, kt) do { _Pragma("unroll") for (int i = 0; i < 4; ++i) { \
;     A_[i] = *(const u32x4*)((const char*)Ap + (aoff + (unsigned)(32 * i * lda + (kt) * 64) * 2u)); B_[i] = *(const u32x4*)((const char*)Wt + (woff + (unsigned)(32 * i * K + (kt) * 64) * 2u)); } } while (0)
; #define BLOAD(A_, B_, kt) do { _Pragma("unroll") for (int i = 0; i < 4; ++i) { \
;     A_[i] = *(const u32x4*)((const char*)Ap + (aoff + (unsigned)(32 * i * lda + (kt) * 64) * 2u)); B_[i] = *(const u32x4*)((const char*)Wt + (woff + (unsigned)(32 * i * K + (kt) * 64) * 2u)); } } while (0)
; #define BSTORE(A_, B_, buf) do { _Pragma("unroll") for (int i = 0; i < 4; ++i) { \
;     *(u32x4*)&As[(buf) * GBUF + (srow + 32 * i) * LDT + sc8] = A_[i]; \
;     *(u32x4*)&Bs[(buf) * GBUF + (srow + 32 * i) * LDT + sc8] = B_[i]; } } while (0)
; template <int NK>
; DI void gemm_run(PF& pf, const u16* __restrict__ Ap, int lda, const u16* __restrict__ Wt, f32x16 (&acc)[2][2], char* smem) {
;     ...
;   __builtin_amdgcn_s_setprio(0);
;   __syncthreads();
;   BSTORE(pf.a0, pf.b0, 0);
;   BLOAD(pf.a0, pf.b0, 2);
;   __syncthreads();
; #pragma unroll
;   for (int kt = 0; kt < nk; kt += 2) {
;     BCOMP(0);
;     BSTORE(pf.a1, pf.b1, 1);
;     if (kt + 3 < nk) BLOAD(pf.a1, pf.b1, kt + 3);
;     __syncthreads();
;     BCOMP(1);
;     if (kt + 2 < nk) { BSTORE(pf.a0, pf.b0, 0); if (kt + 4 < nk) BLOAD(pf.a0, pf.b0, kt + 4); }
;     __syncthreads();
;   }
.Lffn1_kloop:
	s_waitcnt vmcnt(6)
	s_barrier
	ds_read_b128 v[208:211], v138 offset:0
	ds_read_b128 v[224:227], v140 offset:0
	ds_read_b128 v[228:231], v140 offset:1024
	ds_read_b128 v[232:235], v140 offset:2048
	ds_read_b128 v[236:239], v140 offset:3072
	s_add_u32 m0, s42, 0xc000
	s_add_u32 s28, s28, 0x40
	s_addc_u32 s29, s29, 0
	global_load_lds_dwordx4 v142, s[28:29]
	global_load_lds_dwordx4 v143, s[28:29] offset:1024
	s_add_u32 m0, s43, 0xc000
	s_add_u32 s30, s30, 0x40000
	s_addc_u32 s31, s31, 0
	global_load_lds_dwordx4 v144, s[30:31]
	global_load_lds_dwordx4 v145, s[30:31] offset:1024
	global_load_lds_dwordx4 v146, s[30:31] offset:2048
	global_load_lds_dwordx4 v147, s[30:31] offset:3072
	ds_read_b128 v[212:215], v138 offset:1024
	ds_read_b128 v[216:219], v138 offset:2048
	ds_read_b128 v[220:223], v138 offset:3072
	ds_read_b128 v[240:243], v140 offset:8192
	ds_read_b128 v[244:247], v140 offset:9216
	ds_read_b128 v[248:251], v140 offset:10240
	ds_read_b128 v[156:159], v140 offset:11264
	s_waitcnt lgkmcnt(10)
	v_mfma_f32_16x16x32_bf16 v[2:5], v[224:227], v[208:211], v[2:5]
	s_waitcnt lgkmcnt(9)
	v_mfma_f32_16x16x32_bf16 v[6:9], v[228:231], v[208:211], v[6:9]
	s_waitcnt lgkmcnt(8)
	v_mfma_f32_16x16x32_bf16 v[10:13], v[232:235], v[208:211], v[10:13]
	s_waitcnt lgkmcnt(7)
	v_mfma_f32_16x16x32_bf16 v[14:17], v[236:239], v[208:211], v[14:17]
	s_waitcnt lgkmcnt(6)
	v_mfma_f32_16x16x32_bf16 v[18:21], v[224:227], v[212:215], v[18:21]
	v_mfma_f32_16x16x32_bf16 v[22:25], v[228:231], v[212:215], v[22:25]
	v_mfma_f32_16x16x32_bf16 v[26:29], v[232:235], v[212:215], v[26:29]
	v_mfma_f32_16x16x32_bf16 v[30:33], v[236:239], v[212:215], v[30:33]
	s_waitcnt lgkmcnt(5)
	v_mfma_f32_16x16x32_bf16 v[34:37], v[224:227], v[216:219], v[34:37]
	v_mfma_f32_16x16x32_bf16 v[38:41], v[228:231], v[216:219], v[38:41]
	v_mfma_f32_16x16x32_bf16 v[42:45], v[232:235], v[216:219], v[42:45]
	v_mfma_f32_16x16x32_bf16 v[46:49], v[236:239], v[216:219], v[46:49]
	s_waitcnt lgkmcnt(4)
	v_mfma_f32_16x16x32_bf16 v[50:53], v[224:227], v[220:223], v[50:53]
	v_mfma_f32_16x16x32_bf16 v[54:57], v[228:231], v[220:223], v[54:57]
	v_mfma_f32_16x16x32_bf16 v[58:61], v[232:235], v[220:223], v[58:61]
	v_mfma_f32_16x16x32_bf16 v[62:65], v[236:239], v[220:223], v[62:65]
	s_waitcnt lgkmcnt(3)
	v_mfma_f32_16x16x32_bf16 v[74:77], v[240:243], v[208:211], v[74:77]
	s_waitcnt lgkmcnt(2)
	v_mfma_f32_16x16x32_bf16 v[78:81], v[244:247], v[208:211], v[78:81]
	s_waitcnt lgkmcnt(1)
	v_mfma_f32_16x16x32_bf16 v[82:85], v[248:251], v[208:211], v[82:85]
	s_waitcnt lgkmcnt(0)
	v_mfma_f32_16x16x32_bf16 v[86:89], v[156:159], v[208:211], v[86:89]
	v_mfma_f32_16x16x32_bf16 v[90:93], v[240:243], v[212:215], v[90:93]
	v_mfma_f32_16x16x32_bf16 v[94:97], v[244:247], v[212:215], v[94:97]
	v_mfma_f32_16x16x32_bf16 v[98:101], v[248:251], v[212:215], v[98:101]
	v_mfma_f32_16x16x32_bf16 v[102:105], v[156:159], v[212:215], v[102:105]
	v_mfma_f32_16x16x32_bf16 v[106:109], v[240:243], v[216:219], v[106:109]
	v_mfma_f32_16x16x32_bf16 v[110:113], v[244:247], v[216:219], v[110:113]
	v_mfma_f32_16x16x32_bf16 v[114:117], v[248:251], v[216:219], v[114:117]
	v_mfma_f32_16x16x32_bf16 v[118:121], v[156:159], v[216:219], v[118:121]
	v_mfma_f32_16x16x32_bf16 v[122:125], v[240:243], v[220:223], v[122:125]
	v_mfma_f32_16x16x32_bf16 v[126:129], v[244:247], v[220:223], v[126:129]
	v_mfma_f32_16x16x32_bf16 v[130:133], v[248:251], v[220:223], v[130:133]
	v_mfma_f32_16x16x32_bf16 v[134:137], v[156:159], v[220:223], v[134:137]
	s_waitcnt vmcnt(6)
	s_barrier
	ds_read_b128 v[208:211], v138 offset:24576
	ds_read_b128 v[224:227], v140 offset:24576
	ds_read_b128 v[228:231], v140 offset:25600
	ds_read_b128 v[232:235], v140 offset:26624
	ds_read_b128 v[236:239], v140 offset:27648
	s_add_u32 m0, s42, 0x0
	s_add_u32 s28, s28, 0x40
	s_addc_u32 s29, s29, 0
	global_load_lds_dwordx4 v142, s[28:29]
	global_load_lds_dwordx4 v143, s[28:29] offset:1024
	s_add_u32 m0, s43, 0x0
	s_add_u32 s30, s30, 0x40000
	s_addc_u32 s31, s31, 0
	global_load_lds_dwordx4 v144, s[30:31]
	global_load_lds_dwordx4 v145, s[30:31] offset:1024
	global_load_lds_dwordx4 v146, s[30:31] offset:2048
	global_load_lds_dwordx4 v147, s[30:31] offset:3072
	ds_read_b128 v[212:215], v138 offset:25600
	ds_read_b128 v[216:219], v138 offset:26624
	ds_read_b128 v[220:223], v138 offset:27648
	ds_read_b128 v[240:243], v140 offset:32768
	ds_read_b128 v[244:247], v140 offset:33792
	ds_read_b128 v[248:251], v140 offset:34816
	ds_read_b128 v[156:159], v140 offset:35840
	s_waitcnt lgkmcnt(10)
	v_mfma_f32_16x16x32_bf16 v[2:5], v[224:227], v[208:211], v[2:5]
	s_waitcnt lgkmcnt(9)
	v_mfma_f32_16x16x32_bf16 v[6:9], v[228:231], v[208:211], v[6:9]
	s_waitcnt lgkmcnt(8)
	v_mfma_f32_16x16x32_bf16 v[10:13], v[232:235], v[208:211], v[10:13]
	s_waitcnt lgkmcnt(7)
	v_mfma_f32_16x16x32_bf16 v[14:17], v[236:239], v[208:211], v[14:17]
	s_waitcnt lgkmcnt(6)
	v_mfma_f32_16x16x32_bf16 v[18:21], v[224:227], v[212:215], v[18:21]
	v_mfma_f32_16x16x32_bf16 v[22:25], v[228:231], v[212:215], v[22:25]
	v_mfma_f32_16x16x32_bf16 v[26:29], v[232:235], v[212:215], v[26:29]
	v_mfma_f32_16x16x32_bf16 v[30:33], v[236:239], v[212:215], v[30:33]
	s_waitcnt lgkmcnt(5)
	v_mfma_f32_16x16x32_bf16 v[34:37], v[224:227], v[216:219], v[34:37]
	v_mfma_f32_16x16x32_bf16 v[38:41], v[228:231], v[216:219], v[38:41]
	v_mfma_f32_16x16x32_bf16 v[42:45], v[232:235], v[216:219], v[42:45]
	v_mfma_f32_16x16x32_bf16 v[46:49], v[236:239], v[216:219], v[46:49]
	s_waitcnt lgkmcnt(4)
	v_mfma_f32_16x16x32_bf16 v[50:53], v[224:227], v[220:223], v[50:53]
	v_mfma_f32_16x16x32_bf16 v[54:57], v[228:231], v[220:223], v[54:57]
	v_mfma_f32_16x16x32_bf16 v[58:61], v[232:235], v[220:223], v[58:61]
	v_mfma_f32_16x16x32_bf16 v[62:65], v[236:239], v[220:223], v[62:65]
	s_waitcnt lgkmcnt(3)
	v_mfma_f32_16x16x32_bf16 v[74:77], v[240:243], v[208:211], v[74:77]
	s_waitcnt lgkmcnt(2)
	v_mfma_f32_16x16x32_bf16 v[78:81], v[244:247], v[208:211], v[78:81]
	s_waitcnt lgkmcnt(1)
	v_mfma_f32_16x16x32_bf16 v[82:85], v[248:251], v[208:211], v[82:85]
	s_waitcnt lgkmcnt(0)
	v_mfma_f32_16x16x32_bf16 v[86:89], v[156:159], v[208:211], v[86:89]
	v_mfma_f32_16x16x32_bf16 v[90:93], v[240:243], v[212:215], v[90:93]
	v_mfma_f32_16x16x32_bf16 v[94:97], v[244:247], v[212:215], v[94:97]
	v_mfma_f32_16x16x32_bf16 v[98:101], v[248:251], v[212:215], v[98:101]
	v_mfma_f32_16x16x32_bf16 v[102:105], v[156:159], v[212:215], v[102:105]
	v_mfma_f32_16x16x32_bf16 v[106:109], v[240:243], v[216:219], v[106:109]
	v_mfma_f32_16x16x32_bf16 v[110:113], v[244:247], v[216:219], v[110:113]
	v_mfma_f32_16x16x32_bf16 v[114:117], v[248:251], v[216:219], v[114:117]
	v_mfma_f32_16x16x32_bf16 v[118:121], v[156:159], v[216:219], v[118:121]
	v_mfma_f32_16x16x32_bf16 v[122:125], v[240:243], v[220:223], v[122:125]
	v_mfma_f32_16x16x32_bf16 v[126:129], v[244:247], v[220:223], v[126:129]
	v_mfma_f32_16x16x32_bf16 v[130:133], v[248:251], v[220:223], v[130:133]
	v_mfma_f32_16x16x32_bf16 v[134:137], v[156:159], v[220:223], v[134:137]
	s_waitcnt vmcnt(6)
	s_barrier
; #define BLOAD(A_, B_, kt) do { _Pragma("unroll") for (int i = 0; i < 4; ++i) { \
;     A_[i] = *(const u32x4*)((const char*)Ap + (aoff + (unsigned)(32 * i * lda + (kt) * 64) * 2u)); B_[i] = *(const u32x4*)((const char*)Wt + (woff + (unsigned)(32 * i * K + (kt) * 64) * 2u)); } } while (0)
; #define BLOAD(A_, B_, kt) do { _Pragma("unroll") for (int i = 0; i < 4; ++i) { \
;     A_[i] = *(const u32x4*)((const char*)Ap + (aoff + (unsigned)(32 * i * lda + (kt) * 64) * 2u)); B_[i] = *(const u32x4*)((const char*)Wt + (woff + (unsigned)(32 * i * K + (kt) * 64) * 2u)); } } while (0)
; #define BSTORE(A_, B_, buf) do { _Pragma("unroll") for (int i = 0; i < 4; ++i) { \
;     *(u32x4*)&As[(buf) * GBUF + (srow + 32 * i) * LDT + sc8] = A_[i]; \
;     *(u32x4*)&Bs[(buf) * GBUF + (srow + 32 * i) * LDT + sc8] = B_[i]; } } while (0)
; template <int NK>
; DI void gemm_run(PF& pf, const u16* __restrict__ Ap, int lda, const u16* __restrict__ Wt, f32x16 (&acc)[2][2], char* smem) {
;     ...
;   __builtin_amdgcn_s_setprio(0);
;   __syncthreads();
;   BSTORE(pf.a0, pf.b0, 0);
;   BLOAD(pf.a0, pf.b0, 2);
;   __syncthreads();
; #pragma unroll
;   for (int kt = 0; kt < nk; kt += 2) {
;     BCOMP(0);
;     BSTORE(pf.a1, pf.b1, 1);
;     if (kt + 3 < nk) BLOAD(pf.a1, pf.b1, kt + 3);
;     __syncthreads();
;     BCOMP(1);
;     if (kt + 2 < nk) { BSTORE(pf.a0, pf.b0, 0); if (kt + 4 < nk) BLOAD(pf.a0, pf.b0, kt + 4); }
;     __syncthreads();
;   }
	ds_read_b128 v[208:211], v138 offset:49152
	ds_read_b128 v[224:227], v140 offset:49152
	ds_read_b128 v[228:231], v140 offset:50176
	ds_read_b128 v[232:235], v140 offset:51200
	ds_read_b128 v[236:239], v140 offset:52224
	s_add_u32 m0, s42, 0x6000
	s_add_u32 s28, s28, 0x40
	s_addc_u32 s29, s29, 0
	global_load_lds_dwordx4 v142, s[28:29]
	global_load_lds_dwordx4 v143, s[28:29] offset:1024
	s_add_u32 m0, s43, 0x6000
	s_add_u32 s30, s30, 0x40000
	s_addc_u32 s31, s31, 0
	global_load_lds_dwordx4 v144, s[30:31]
	global_load_lds_dwordx4 v145, s[30:31] offset:1024
	global_load_lds_dwordx4 v146, s[30:31] offset:2048
	global_load_lds_dwordx4 v147, s[30:31] offset:3072
	ds_read_b128 v[212:215], v138 offset:50176
	ds_read_b128 v[216:219], v138 offset:51200
	ds_read_b128 v[220:223], v138 offset:52224
	ds_read_b128 v[240:243], v140 offset:57344
	ds_read_b128 v[244:247], v140 offset:58368
	ds_read_b128 v[248:251], v140 offset:59392
	ds_read_b128 v[156:159], v140 offset:60416
	s_waitcnt lgkmcnt(10)
	v_mfma_f32_16x16x32_bf16 v[2:5], v[224:227], v[208:211], v[2:5]
	s_waitcnt lgkmcnt(9)
	v_mfma_f32_16x16x32_bf16 v[6:9], v[228:231], v[208:211], v[6:9]
	s_waitcnt lgkmcnt(8)
	v_mfma_f32_16x16x32_bf16 v[10:13], v[232:235], v[208:211], v[10:13]
	s_waitcnt lgkmcnt(7)
	v_mfma_f32_16x16x32_bf16 v[14:17], v[236:239], v[208:211], v[14:17]
	s_waitcnt lgkmcnt(6)
	v_mfma_f32_16x16x32_bf16 v[18:21], v[224:227], v[212:215], v[18:21]
	v_mfma_f32_16x16x32_bf16 v[22:25], v[228:231], v[212:215], v[22:25]
	v_mfma_f32_16x16x32_bf16 v[26:29], v[232:235], v[212:215], v[26:29]
	v_mfma_f32_16x16x32_bf16 v[30:33], v[236:239], v[212:215], v[30:33]
	s_waitcnt lgkmcnt(5)
	v_mfma_f32_16x16x32_bf16 v[34:37], v[224:227], v[216:219], v[34:37]
	v_mfma_f32_16x16x32_bf16 v[38:41], v[228:231], v[216:219], v[38:41]
	v_mfma_f32_16x16x32_bf16 v[42:45], v[232:235], v[216:219], v[42:45]
	v_mfma_f32_16x16x32_bf16 v[46:49], v[236:239], v[216:219], v[46:49]
	s_waitcnt lgkmcnt(4)
	v_mfma_f32_16x16x32_bf16 v[50:53], v[224:227], v[220:223], v[50:53]
	v_mfma_f32_16x16x32_bf16 v[54:57], v[228:231], v[220:223], v[54:57]
	v_mfma_f32_16x16x32_bf16 v[58:61], v[232:235], v[220:223], v[58:61]
	v_mfma_f32_16x16x32_bf16 v[62:65], v[236:239], v[220:223], v[62:65]
	s_waitcnt lgkmcnt(3)
	v_mfma_f32_16x16x32_bf16 v[74:77], v[240:243], v[208:211], v[74:77]
	s_waitcnt lgkmcnt(2)
	v_mfma_f32_16x16x32_bf16 v[78:81], v[244:247], v[208:211], v[78:81]
	s_waitcnt lgkmcnt(1)
	v_mfma_f32_16x16x32_bf16 v[82:85], v[248:251], v[208:211], v[82:85]
	s_waitcnt lgkmcnt(0)
	v_mfma_f32_16x16x32_bf16 v[86:89], v[156:159], v[208:211], v[86:89]
	v_mfma_f32_16x16x32_bf16 v[90:93], v[240:243], v[212:215], v[90:93]
	v_mfma_f32_16x16x32_bf16 v[94:97], v[244:247], v[212:215], v[94:97]
	v_mfma_f32_16x16x32_bf16 v[98:101], v[248:251], v[212:215], v[98:101]
	v_mfma_f32_16x16x32_bf16 v[102:105], v[156:159], v[212:215], v[102:105]
	v_mfma_f32_16x16x32_bf16 v[106:109], v[240:243], v[216:219], v[106:109]
	v_mfma_f32_16x16x32_bf16 v[110:113], v[244:247], v[216:219], v[110:113]
	v_mfma_f32_16x16x32_bf16 v[114:117], v[248:251], v[216:219], v[114:117]
	v_mfma_f32_16x16x32_bf16 v[118:121], v[156:159], v[216:219], v[118:121]
	v_mfma_f32_16x16x32_bf16 v[122:125], v[240:243], v[220:223], v[122:125]
	v_mfma_f32_16x16x32_bf16 v[126:129], v[244:247], v[220:223], v[126:129]
	v_mfma_f32_16x16x32_bf16 v[130:133], v[248:251], v[220:223], v[130:133]
	v_mfma_f32_16x16x32_bf16 v[134:137], v[156:159], v[220:223], v[134:137]
	s_sub_u32 s46, s46, 1
	s_cmp_lg_u32 s46, 0
	s_cbranch_scc1 .Lffn1_kloop
	s_waitcnt vmcnt(6)
	s_barrier
; #define BLOAD(A_, B_, kt) do { _Pragma("unroll") for (int i = 0; i < 4; ++i) { \
;     A_[i] = *(const u32x4*)((const char*)Ap + (aoff + (unsigned)(32 * i * lda + (kt) * 64) * 2u)); B_[i] = *(const u32x4*)((const char*)Wt + (woff + (unsigned)(32 * i * K + (kt) * 64) * 2u)); } } while (0)
; #define BLOAD(A_, B_, kt) do { _Pragma("unroll") for (int i = 0; i < 4; ++i) { \
;     A_[i] = *(const u32x4*)((const char*)Ap + (aoff + (unsigned)(32 * i * lda + (kt) * 64) * 2u)); B_[i] = *(const u32x4*)((const char*)Wt + (woff + (unsigned)(32 * i * K + (kt) * 64) * 2u)); } } while (0)
; #define BSTORE(A_, B_, buf) do { _Pragma("unroll") for (int i = 0; i < 4; ++i) { \
;     *(u32x4*)&As[(buf) * GBUF + (srow + 32 * i) * LDT + sc8] = A_[i]; \
;     *(u32x4*)&Bs[(buf) * GBUF + (srow + 32 * i) * LDT + sc8] = B_[i]; } } while (0)
; template <int NK>
; DI void gemm_run(PF& pf, const u16* __restrict__ Ap, int lda, const u16* __restrict__ Wt, f32x16 (&acc)[2][2], char* smem) {
;     ...
; #pragma unroll
;   for (int kt = 0; kt < nk; kt += 2) {
;     BCOMP(0);
;     BSTORE(pf.a1, pf.b1, 1);
;     if (kt + 3 < nk) BLOAD(pf.a1, pf.b1, kt + 3);
;     __syncthreads();
;     BCOMP(1);
;     if (kt + 2 < nk) { BSTORE(pf.a0, pf.b0, 0); if (kt + 4 < nk) BLOAD(pf.a0, pf.b0, kt + 4); }
;     __syncthreads();
;   }
	ds_read_b128 v[208:211], v138 offset:0
	ds_read_b128 v[224:227], v140 offset:0
	ds_read_b128 v[228:231], v140 offset:1024
	ds_read_b128 v[232:235], v140 offset:2048
	ds_read_b128 v[236:239], v140 offset:3072
	ds_read_b128 v[212:215], v138 offset:1024
	ds_read_b128 v[216:219], v138 offset:2048
	ds_read_b128 v[220:223], v138 offset:3072
	ds_read_b128 v[240:243], v140 offset:8192
	ds_read_b128 v[244:247], v140 offset:9216
	ds_read_b128 v[248:251], v140 offset:10240
	ds_read_b128 v[156:159], v140 offset:11264
	s_waitcnt lgkmcnt(10)
	v_mfma_f32_16x16x32_bf16 v[2:5], v[224:227], v[208:211], v[2:5]
	s_waitcnt lgkmcnt(9)
	v_mfma_f32_16x16x32_bf16 v[6:9], v[228:231], v[208:211], v[6:9]
	s_waitcnt lgkmcnt(8)
	v_mfma_f32_16x16x32_bf16 v[10:13], v[232:235], v[208:211], v[10:13]
	s_waitcnt lgkmcnt(7)
	v_mfma_f32_16x16x32_bf16 v[14:17], v[236:239], v[208:211], v[14:17]
	s_waitcnt lgkmcnt(6)
	v_mfma_f32_16x16x32_bf16 v[18:21], v[224:227], v[212:215], v[18:21]
	v_mfma_f32_16x16x32_bf16 v[22:25], v[228:231], v[212:215], v[22:25]
	v_mfma_f32_16x16x32_bf16 v[26:29], v[232:235], v[212:215], v[26:29]
	v_mfma_f32_16x16x32_bf16 v[30:33], v[236:239], v[212:215], v[30:33]
	s_waitcnt lgkmcnt(5)
	v_mfma_f32_16x16x32_bf16 v[34:37], v[224:227], v[216:219], v[34:37]
	v_mfma_f32_16x16x32_bf16 v[38:41], v[228:231], v[216:219], v[38:41]
	v_mfma_f32_16x16x32_bf16 v[42:45], v[232:235], v[216:219], v[42:45]
	v_mfma_f32_16x16x32_bf16 v[46:49], v[236:239], v[216:219], v[46:49]
	s_waitcnt lgkmcnt(4)
	v_mfma_f32_16x16x32_bf16 v[50:53], v[224:227], v[220:223], v[50:53]
	v_mfma_f32_16x16x32_bf16 v[54:57], v[228:231], v[220:223], v[54:57]
	v_mfma_f32_16x16x32_bf16 v[58:61], v[232:235], v[220:223], v[58:61]
	v_mfma_f32_16x16x32_bf16 v[62:65], v[236:239], v[220:223], v[62:65]
	s_waitcnt lgkmcnt(3)
	v_mfma_f32_16x16x32_bf16 v[74:77], v[240:243], v[208:211], v[74:77]
	s_waitcnt lgkmcnt(2)
	v_mfma_f32_16x16x32_bf16 v[78:81], v[244:247], v[208:211], v[78:81]
	s_waitcnt lgkmcnt(1)
	v_mfma_f32_16x16x32_bf16 v[82:85], v[248:251], v[208:211], v[82:85]
	s_waitcnt lgkmcnt(0)
	v_mfma_f32_16x16x32_bf16 v[86:89], v[156:159], v[208:211], v[86:89]
	v_mfma_f32_16x16x32_bf16 v[90:93], v[240:243], v[212:215], v[90:93]
	v_mfma_f32_16x16x32_bf16 v[94:97], v[244:247], v[212:215], v[94:97]
	v_mfma_f32_16x16x32_bf16 v[98:101], v[248:251], v[212:215], v[98:101]
	v_mfma_f32_16x16x32_bf16 v[102:105], v[156:159], v[212:215], v[102:105]
	v_mfma_f32_16x16x32_bf16 v[106:109], v[240:243], v[216:219], v[106:109]
	v_mfma_f32_16x16x32_bf16 v[110:113], v[244:247], v[216:219], v[110:113]
	v_mfma_f32_16x16x32_bf16 v[114:117], v[248:251], v[216:219], v[114:117]
	v_mfma_f32_16x16x32_bf16 v[118:121], v[156:159], v[216:219], v[118:121]
	v_mfma_f32_16x16x32_bf16 v[122:125], v[240:243], v[220:223], v[122:125]
	v_mfma_f32_16x16x32_bf16 v[126:129], v[244:247], v[220:223], v[126:129]
	v_mfma_f32_16x16x32_bf16 v[130:133], v[248:251], v[220:223], v[130:133]
	v_mfma_f32_16x16x32_bf16 v[134:137], v[156:159], v[220:223], v[134:137]
	s_waitcnt vmcnt(0)
	s_barrier
	ds_read_b128 v[208:211], v138 offset:24576
	ds_read_b128 v[224:227], v140 offset:24576
	ds_read_b128 v[228:231], v140 offset:25600
	ds_read_b128 v[232:235], v140 offset:26624
	ds_read_b128 v[236:239], v140 offset:27648
	ds_read_b128 v[212:215], v138 offset:25600
	ds_read_b128 v[216:219], v138 offset:26624
	ds_read_b128 v[220:223], v138 offset:27648
	ds_read_b128 v[240:243], v140 offset:32768
	ds_read_b128 v[244:247], v140 offset:33792
	ds_read_b128 v[248:251], v140 offset:34816
	ds_read_b128 v[156:159], v140 offset:35840
	s_waitcnt lgkmcnt(10)
	v_mfma_f32_16x16x32_bf16 v[2:5], v[224:227], v[208:211], v[2:5]
	s_waitcnt lgkmcnt(9)
	v_mfma_f32_16x16x32_bf16 v[6:9], v[228:231], v[208:211], v[6:9]
	s_waitcnt lgkmcnt(8)
	v_mfma_f32_16x16x32_bf16 v[10:13], v[232:235], v[208:211], v[10:13]
	s_waitcnt lgkmcnt(7)
	v_mfma_f32_16x16x32_bf16 v[14:17], v[236:239], v[208:211], v[14:17]
	s_waitcnt lgkmcnt(6)
	v_mfma_f32_16x16x32_bf16 v[18:21], v[224:227], v[212:215], v[18:21]
	v_mfma_f32_16x16x32_bf16 v[22:25], v[228:231], v[212:215], v[22:25]
	v_mfma_f32_16x16x32_bf16 v[26:29], v[232:235], v[212:215], v[26:29]
	v_mfma_f32_16x16x32_bf16 v[30:33], v[236:239], v[212:215], v[30:33]
	s_waitcnt lgkmcnt(5)
	v_mfma_f32_16x16x32_bf16 v[34:37], v[224:227], v[216:219], v[34:37]
	v_mfma_f32_16x16x32_bf16 v[38:41], v[228:231], v[216:219], v[38:41]
	v_mfma_f32_16x16x32_bf16 v[42:45], v[232:235], v[216:219], v[42:45]
	v_mfma_f32_16x16x32_bf16 v[46:49], v[236:239], v[216:219], v[46:49]
	s_waitcnt lgkmcnt(4)
	v_mfma_f32_16x16x32_bf16 v[50:53], v[224:227], v[220:223], v[50:53]
	v_mfma_f32_16x16x32_bf16 v[54:57], v[228:231], v[220:223], v[54:57]
	v_mfma_f32_16x16x32_bf16 v[58:61], v[232:235], v[220:223], v[58:61]
	v_mfma_f32_16x16x32_bf16 v[62:65], v[236:239], v[220:223], v[62:65]
	s_waitcnt lgkmcnt(3)
	v_mfma_f32_16x16x32_bf16 v[74:77], v[240:243], v[208:211], v[74:77]
	s_waitcnt lgkmcnt(2)
	v_mfma_f32_16x16x32_bf16 v[78:81], v[244:247], v[208:211], v[78:81]
	s_waitcnt lgkmcnt(1)
	v_mfma_f32_16x16x32_bf16 v[82:85], v[248:251], v[208:211], v[82:85]
	s_waitcnt lgkmcnt(0)
	v_mfma_f32_16x16x32_bf16 v[86:89], v[156:159], v[208:211], v[86:89]
	v_mfma_f32_16x16x32_bf16 v[90:93], v[240:243], v[212:215], v[90:93]
	v_mfma_f32_16x16x32_bf16 v[94:97], v[244:247], v[212:215], v[94:97]
	v_mfma_f32_16x16x32_bf16 v[98:101], v[248:251], v[212:215], v[98:101]
	v_mfma_f32_16x16x32_bf16 v[102:105], v[156:159], v[212:215], v[102:105]
	v_mfma_f32_16x16x32_bf16 v[106:109], v[240:243], v[216:219], v[106:109]
	v_mfma_f32_16x16x32_bf16 v[110:113], v[244:247], v[216:219], v[110:113]
	v_mfma_f32_16x16x32_bf16 v[114:117], v[248:251], v[216:219], v[114:117]
	v_mfma_f32_16x16x32_bf16 v[118:121], v[156:159], v[216:219], v[118:121]
	v_mfma_f32_16x16x32_bf16 v[122:125], v[240:243], v[220:223], v[122:125]
	v_mfma_f32_16x16x32_bf16 v[126:129], v[244:247], v[220:223], v[126:129]
	v_mfma_f32_16x16x32_bf16 v[130:133], v[248:251], v[220:223], v[130:133]
	v_mfma_f32_16x16x32_bf16 v[134:137], v[156:159], v[220:223], v[134:137]
	s_barrier
